# EpiResid (out-proj, down): 8-consecutive-column accumulator layout via permuted B-fragment LDS rows; 16-byte base loads and bf16 stores, batched ssq reduction
# speedup vs baseline: 1.0163x; 1.0163x over previous
; __device__ __forceinline__ int fresh_tid() { int t = threadIdx.x; asm volatile("" : "+v"(t)); return t; }
; #define PG8_STAGE(bufoff, gbase, voff) do { _Pragma("unroll") for (int _i = 0; _i < 2; ++_i) \
;         __builtin_amdgcn_global_load_lds((const unsigned*)((const char*)(gbase) + (voff)[_i]), (LAS unsigned*)(lds + (bufoff) + ldsw + _i * 8192), 16, 0, 0); } while (0)
; #define PG8_WAIT_V(n) asm volatile("s_waitcnt vmcnt(" #n ")" ::: "memory")
; template <class Epi, class Sched, int NSEG, int KK, int LDA, int LDB>
; __device__ __forceinline__ void gemm_phase(LAS unsigned char* lds, const Gemm g, const Sched& S, const Epi& E) {
;     const int tid = fresh_tid(), wid = __builtin_amdgcn_readfirstlane(tid >> 6), lane = tid & 63, wr = wid >> 2, wc = wid & 3, fr = lane & 15, fq = lane >> 4;
;     constexpr int nt = KK / BK;
;     unsigned voffA[2], voffB[2];
; #pragma unroll
;     for (int i = 0; i < 2; ++i) { int R, C; stage_rc(tid * 16 + i * 8192, R, C); const int Rb = Epi::PERM ? ((R & ~31) + perm32(R & 31)) : R;
;         voffA[i] = (unsigned)(R * LDA + C) * 2u; voffB[i] = (unsigned)(Rb * LDB + C) * 2u; }
;     constexpr size_t kstep = (size_t)(BK * 2);
;     constexpr size_t hstepA = (size_t)HALF * LDA * 2, hstepB = (size_t)HALF * LDB * 2;
;     constexpr size_t tstepA = 2 * hstepA, tstepB = 2 * hstepB;
;     const unsigned ldsw = (unsigned)wid * 1024u;
;     const int aoff = lds_byte(wr * 64 + fr, fq * 8), boff = lds_byte(wc * 32 + fr, fq * 8);
;     ...
;     Unit cur, nxt; int ui = 0;
;     if (!S.next(0, cur)) return;
;     f32x4 acc[2][2][4][2];
; #pragma unroll
;     for (int a = 0; a < 2; ++a)
; #pragma unroll
;         for (int b = 0; b < 2; ++b)
; #pragma unroll
;             for (int m = 0; m < 4; ++m)
; #pragma unroll
;                 for (int n = 0; n < 2; ++n) acc[a][b][m][n] = (f32x4){0.f, 0.f, 0.f, 0.f};
;     bf16x8 At[4][2], B0[2][2], B1[2][2];
;     const char* cA = PG8_APTR(cur); const char* cB = PG8_BPTR(cur);
;     PG8_STAGE(PG8_SB(0, 0), cB, voffB); PG8_STAGE(PG8_SB(0, 1), cB + hstepB, voffB); PG8_STAGE(PG8_SA(0, 0), cA, voffA); PG8_STAGE(PG8_SA(0, 1), cA + hstepA, voffA);
;     if (wr == 1) PG8_BAR;
;     PG8_WAIT_V(2); PG8_BAR;
;     PG8_STAGE(PG8_SB(1, 0), cB + kstep, voffB); PG8_STAGE(PG8_SA(1, 0), cA + kstep, voffA); PG8_STAGE(PG8_SB(1, 1), cB + hstepB + kstep, voffB);
;     PG8_WAIT_V(6); PG8_BAR;
.LBB0_975:
	v_and_b32_e32 v9, 15, v8
	v_and_b32_e32 v18, 48, v8
	v_lshlrev_b32_e32 v8, 2, v8
	s_and_b32 s56, s9, 3
	v_lshl_or_b32 v9, v9, 6, v18
	s_lshl_b32 s9, s22, 13
	v_and_b32_e32 v8, 32, v8
	v_lshl_add_u64 v[10:11], s[44:45], 0, v[0:1]
	v_mov_b32_e32 v131, v1
	v_readlane_b32 s40, v255, 63
	v_bitop3_b32 v18, v9, s9, v8 bitop3:0xde
	s_lshl_b32 s9, s56, 12
	v_lshl_add_u64 v[12:13], s[44:45], 0, v[130:131]
	v_readlane_b32 s41, v254, 0
	v_bitop3_b32 v164, v9, s9, v8 bitop3:0xde
	v_and_b32_e32 v218, 3, v246
	v_bfe_u32 v219, v246, 2, 1
	v_bfe_u32 v220, v246, 3, 1
	v_bfe_u32 v221, v246, 4, 2
	v_lshlrev_b32_e32 v218, 6, v218
	v_lshl_or_b32 v218, v219, 9, v218
	v_lshl_or_b32 v218, v221, 4, v218
	v_lshlrev_b32_e32 v219, 5, v219
	v_xor_b32_e32 v218, v218, v219
	v_lshl_or_b32 v218, v220, 11, v218
	v_or_b32_e32 v164, s9, v218
	s_add_i32 m0, s26, 0x18000
	v_lshl_add_u64 v[8:9], v[10:11], 0, s[28:29]
	v_lshl_add_u64 v[14:15], s[40:41], 0, v[0:1]
	s_waitcnt vmcnt(2)
	s_barrier
	global_load_lds_dwordx4 v[8:9], off
	v_lshl_add_u64 v[8:9], v[12:13], 0, s[28:29]
	s_add_i32 m0, s26, 0x1a000
	s_add_i32 s57, s26, 0x8000
	s_add_i32 s58, s26, 0xa000
	v_lshl_add_u64 v[16:17], s[40:41], 0, v[130:131]
	global_load_lds_dwordx4 v[8:9], off
	v_lshl_add_u64 v[8:9], v[14:15], 0, s[28:29]
	s_mov_b32 m0, s57
	s_add_u32 s10, s44, 0x40080
	global_load_lds_dwordx4 v[8:9], off
	v_lshl_add_u64 v[8:9], v[16:17], 0, s[28:29]
	s_mov_b32 m0, s58
	s_addc_u32 s11, s45, 0
	global_load_lds_dwordx4 v[8:9], off
	s_add_i32 m0, s26, 0x1c000
	v_lshl_add_u64 v[8:9], s[10:11], 0, v[0:1]
	global_load_lds_dwordx4 v[8:9], off
	v_lshl_add_u64 v[8:9], s[10:11], 0, v[130:131]
	s_add_i32 m0, s26, 0x1e000
	v_readlane_b32 s10, v255, 46
	global_load_lds_dwordx4 v[8:9], off
	v_lshlrev_b32_e32 v8, 14, v5
	v_and_b32_e32 v8, 0xffff8000, v8
	v_lshl_add_u32 v6, v6, 11, v8
	v_and_b32_e32 v5, 1, v5
	v_lshl_or_b32 v5, v5, 6, v6
	v_lshl_add_u32 v132, v7, 1, v5
	v_lshlrev_b32_e32 v5, 14, v2
	v_and_b32_e32 v5, 0xffff8000, v5
	s_waitcnt vmcnt(6)
	v_lshl_add_u32 v3, v3, 11, v5
	v_and_b32_e32 v2, 1, v2
	s_mov_b32 s24, s10
	v_readlane_b32 s10, v254, 3
	s_cmpk_lt_u32 s8, 0x100
	v_lshl_or_b32 v2, v2, 6, v3
	v_readlane_b32 s11, v254, 4
	s_cselect_b64 s[8:9], -1, 0
	v_mov_b32_e32 v133, v1
	v_lshl_add_u32 v134, v4, 1, v2
	v_mov_b32_e32 v135, v1
	s_mov_b32 s59, 0
	v_add_u32_e32 v165, 0, v18
	s_mov_b32 s25, s10
	s_mov_b64 s[10:11], s[40:41]
	s_barrier
	s_branch .LBB0_978

; #define PG8_STAGE(bufoff, gbase, voff) do { _Pragma("unroll") for (int _i = 0; _i < 2; ++_i) \
;         __builtin_amdgcn_global_load_lds((const unsigned*)((const char*)(gbase) + (voff)[_i]), (LAS unsigned*)(lds + (bufoff) + ldsw + _i * 8192), 16, 0, 0); } while (0)
; #define PG8_LDA(dst, b, h) do { _Pragma("unroll") for (int m = 0; m < 4; ++m) _Pragma("unroll") for (int k = 0; k < 2; ++k) dst[m][k] = *(const LAS bf16x8*)(lds + PG8_SA(b, h) + aoff + m * 2048 + k * 1024); } while (0)
; #define PG8_LDB(dst, b, h) do { _Pragma("unroll") for (int n = 0; n < 2; ++n) _Pragma("unroll") for (int k = 0; k < 2; ++k) dst[n][k] = *(const LAS bf16x8*)(lds + PG8_SB(b, h) + boff + n * 2048 + k * 1024); } while (0)
; #define PG8_MMA(ai, bj, At, Bt) do { __builtin_amdgcn_s_setprio(1); _Pragma("unroll") for (int m = 0; m < 4; ++m) _Pragma("unroll") for (int n = 0; n < 2; ++n) _Pragma("unroll") for (int k = 0; k < 2; ++k) \
;         acc[ai][bj][m][n] = __builtin_amdgcn_mfma_f32_16x16x32_bf16(Bt[n][k], At[m][k], acc[ai][bj][m][n], 0, 0, 0); __builtin_amdgcn_s_setprio(0); } while (0)
; #define PG8_WAIT_V(n) asm volatile("s_waitcnt vmcnt(" #n ")" ::: "memory")
; #define PG8_WAIT_L(n) asm volatile("s_waitcnt lgkmcnt(" #n ")" ::: "memory")
; #define PG8_BAR __builtin_amdgcn_s_barrier()
; #define PG8_SCHED __builtin_amdgcn_sched_barrier(0)
; template <class Epi, class Sched, int NSEG, int KK, int LDA, int LDB>
; __device__ __forceinline__ void gemm_phase(LAS unsigned char* lds, const Gemm g, const Sched& S, const Epi& E) {
;     ...
;             const char* a1 = cA + (size_t)(t + 1) * kstep;
;             const char* a2 = last ? nA : cA + (size_t)(t + 2) * kstep; const char* b2 = last ? nB : cB + (size_t)(t + 2) * kstep;
;             const char* a3 = a2 + kstep; const char* b3 = b2 + kstep;
;             PG8_LDB(B0, 0, 0); PG8_LDB(B1, 0, 1); PG8_SCHED; PG8_LDA(At, 0, 0); PG8_STAGE(PG8_SA(1, 1), a1 + hstepA, voffA);
;             PG8_WAIT_V(8); PG8_WAIT_L(0); PG8_BAR; PG8_MMA(0, 0, At, B0); PG8_MMA(0, 1, At, B1); PG8_BAR; PG8_SCHED;
;             PG8_LDA(At, 0, 1); PG8_STAGE(PG8_SB(0, 0), b2, voffB); PG8_STAGE(PG8_SB(0, 1), b2 + hstepB, voffB); PG8_STAGE(PG8_SA(0, 0), a2, voffA);
.LBB0_985:
	s_add_u32 s10, s42, 0xfffc0080
	s_addc_u32 s11, s43, -1
	s_add_i32 s63, 0, 0x10000
	s_cmp_eq_u32 s62, 12
	s_cselect_b32 s45, s49, s11
	s_cselect_b32 s44, s54, s10
	s_cselect_b32 s11, s47, s61
	s_cselect_b32 s10, s55, s60
	s_add_i32 s77, 0, 0x14000
	v_add_u32_e32 v148, s63, v164
	v_add_u32_e32 v166, s77, v164
	ds_read_b128 v[136:139], v148
	ds_read_b128 v[140:143], v148 offset:1024
	ds_read_b128 v[144:147], v148 offset:256
	ds_read_b128 v[148:151], v148 offset:1280
	ds_read_b128 v[152:155], v166
	ds_read_b128 v[156:159], v166 offset:1024
	ds_read_b128 v[160:163], v166 offset:256
	ds_read_b128 v[176:179], v166 offset:1280
	v_lshl_add_u64 v[166:167], s[42:43], 0, v[132:133]
	s_add_i32 m0, s26, 0xc000
	ds_read_b128 v[180:183], v165
	ds_read_b128 v[184:187], v165 offset:1024
	ds_read_b128 v[188:191], v165 offset:2048
	ds_read_b128 v[192:195], v165 offset:3072
	ds_read_b128 v[196:199], v165 offset:4096
	ds_read_b128 v[200:203], v165 offset:5120
	ds_read_b128 v[204:207], v165 offset:6144
	ds_read_b128 v[208:211], v165 offset:7168
	global_load_lds_dwordx4 v[166:167], off
	v_lshl_add_u64 v[166:167], s[42:43], 0, v[134:135]
	s_add_i32 m0, s26, 0xe000
	s_nop 0
	global_load_lds_dwordx4 v[166:167], off
	s_waitcnt vmcnt(8)
	s_waitcnt lgkmcnt(0)
	s_barrier
	s_setprio 1
	s_waitcnt lgkmcnt(0)
	v_mfma_f32_16x16x32_bf16 v[126:129], v[136:139], v[180:183], v[126:129]
	v_mfma_f32_16x16x32_bf16 v[122:125], v[144:147], v[180:183], v[122:125]
	v_mfma_f32_16x16x32_bf16 v[110:113], v[136:139], v[188:191], v[110:113]
	v_mfma_f32_16x16x32_bf16 v[106:109], v[144:147], v[188:191], v[106:109]
	v_mfma_f32_16x16x32_bf16 v[94:97], v[136:139], v[196:199], v[94:97]
	v_mfma_f32_16x16x32_bf16 v[90:93], v[144:147], v[196:199], v[90:93]
	v_mfma_f32_16x16x32_bf16 v[78:81], v[136:139], v[204:207], v[78:81]
	v_mfma_f32_16x16x32_bf16 v[74:77], v[144:147], v[204:207], v[74:77]
	v_mfma_f32_16x16x32_bf16 v[126:129], v[140:143], v[184:187], v[126:129]
	v_mfma_f32_16x16x32_bf16 v[122:125], v[148:151], v[184:187], v[122:125]
	v_mfma_f32_16x16x32_bf16 v[110:113], v[140:143], v[192:195], v[110:113]
	v_mfma_f32_16x16x32_bf16 v[106:109], v[148:151], v[192:195], v[106:109]
	v_mfma_f32_16x16x32_bf16 v[94:97], v[140:143], v[200:203], v[94:97]
	v_mfma_f32_16x16x32_bf16 v[90:93], v[148:151], v[200:203], v[90:93]
	v_mfma_f32_16x16x32_bf16 v[78:81], v[140:143], v[208:211], v[78:81]
	v_mfma_f32_16x16x32_bf16 v[74:77], v[148:151], v[208:211], v[74:77]
	s_setprio 0
	s_setprio 1
	v_mfma_f32_16x16x32_bf16 v[118:121], v[152:155], v[180:183], v[118:121]
	v_mfma_f32_16x16x32_bf16 v[114:117], v[160:163], v[180:183], v[114:117]
	v_mfma_f32_16x16x32_bf16 v[102:105], v[152:155], v[188:191], v[102:105]
	v_mfma_f32_16x16x32_bf16 v[98:101], v[160:163], v[188:191], v[98:101]
	v_mfma_f32_16x16x32_bf16 v[86:89], v[152:155], v[196:199], v[86:89]
	v_mfma_f32_16x16x32_bf16 v[82:85], v[160:163], v[196:199], v[82:85]
	v_mfma_f32_16x16x32_bf16 v[70:73], v[152:155], v[204:207], v[70:73]
	v_mfma_f32_16x16x32_bf16 v[66:69], v[160:163], v[204:207], v[66:69]
	v_mfma_f32_16x16x32_bf16 v[118:121], v[156:159], v[184:187], v[118:121]
	v_mfma_f32_16x16x32_bf16 v[114:117], v[176:179], v[184:187], v[114:117]
	v_mfma_f32_16x16x32_bf16 v[102:105], v[156:159], v[192:195], v[102:105]
	v_mfma_f32_16x16x32_bf16 v[98:101], v[176:179], v[192:195], v[98:101]
	v_mfma_f32_16x16x32_bf16 v[86:89], v[156:159], v[200:203], v[86:89]
	v_mfma_f32_16x16x32_bf16 v[82:85], v[176:179], v[200:203], v[82:85]
	v_mfma_f32_16x16x32_bf16 v[70:73], v[156:159], v[208:211], v[70:73]
	v_mfma_f32_16x16x32_bf16 v[66:69], v[176:179], v[208:211], v[66:69]
	s_setprio 0
	s_barrier
	s_add_i32 s63, s63, s23
	v_lshl_add_u64 v[166:167], s[10:11], 0, v[0:1]
	s_mov_b32 m0, s63
	ds_read_b128 v[180:183], v165 offset:16384
	ds_read_b128 v[184:187], v165 offset:17408
	ds_read_b128 v[188:191], v165 offset:18432
	ds_read_b128 v[192:195], v165 offset:19456
	ds_read_b128 v[196:199], v165 offset:20480
	ds_read_b128 v[200:203], v165 offset:21504
	ds_read_b128 v[204:207], v165 offset:22528
	ds_read_b128 v[208:211], v165 offset:23552
	global_load_lds_dwordx4 v[166:167], off
	s_add_i32 m0, s63, 0x2000
	s_add_u32 s94, s10, 0x40000
	v_lshl_add_u64 v[172:173], s[10:11], 0, v[130:131]
	s_addc_u32 s95, s11, 0
	s_add_i32 s63, s77, s23
	global_load_lds_dwordx4 v[172:173], off
	v_lshl_add_u64 v[212:213], s[94:95], 0, v[0:1]
	s_mov_b32 m0, s63
	v_lshl_add_u64 v[214:215], s[44:45], 0, v[130:131]
	global_load_lds_dwordx4 v[212:213], off
	v_lshl_add_u64 v[212:213], s[94:95], 0, v[130:131]
	s_add_i32 m0, s63, 0x2000
	s_nop 0
	global_load_lds_dwordx4 v[212:213], off
	v_lshl_add_u64 v[212:213], s[44:45], 0, v[0:1]
	s_mov_b32 m0, s26
	s_nop 0
	global_load_lds_dwordx4 v[212:213], off
	s_mov_b32 m0, s33
	s_nop 0
	global_load_lds_dwordx4 v[214:215], off
	s_waitcnt vmcnt(8)
	s_waitcnt lgkmcnt(0)
	s_barrier
; #define PG8_STAGE(bufoff, gbase, voff) do { _Pragma("unroll") for (int _i = 0; _i < 2; ++_i) \
;         __builtin_amdgcn_global_load_lds((const unsigned*)((const char*)(gbase) + (voff)[_i]), (LAS unsigned*)(lds + (bufoff) + ldsw + _i * 8192), 16, 0, 0); } while (0)
; #define PG8_LDA(dst, b, h) do { _Pragma("unroll") for (int m = 0; m < 4; ++m) _Pragma("unroll") for (int k = 0; k < 2; ++k) dst[m][k] = *(const LAS bf16x8*)(lds + PG8_SA(b, h) + aoff + m * 2048 + k * 1024); } while (0)
; #define PG8_LDB(dst, b, h) do { _Pragma("unroll") for (int n = 0; n < 2; ++n) _Pragma("unroll") for (int k = 0; k < 2; ++k) dst[n][k] = *(const LAS bf16x8*)(lds + PG8_SB(b, h) + boff + n * 2048 + k * 1024); } while (0)
; #define PG8_MMA(ai, bj, At, Bt) do { __builtin_amdgcn_s_setprio(1); _Pragma("unroll") for (int m = 0; m < 4; ++m) _Pragma("unroll") for (int n = 0; n < 2; ++n) _Pragma("unroll") for (int k = 0; k < 2; ++k) \
;         acc[ai][bj][m][n] = __builtin_amdgcn_mfma_f32_16x16x32_bf16(Bt[n][k], At[m][k], acc[ai][bj][m][n], 0, 0, 0); __builtin_amdgcn_s_setprio(0); } while (0)
; #define PG8_WAIT_V(n) asm volatile("s_waitcnt vmcnt(" #n ")" ::: "memory")
; #define PG8_WAIT_L(n) asm volatile("s_waitcnt lgkmcnt(" #n ")" ::: "memory")
; #define PG8_BAR __builtin_amdgcn_s_barrier()
; #define PG8_SCHED __builtin_amdgcn_sched_barrier(0)
; template <class Epi, class Sched, int NSEG, int KK, int LDA, int LDB>
; __device__ __forceinline__ void gemm_phase(LAS unsigned char* lds, const Gemm g, const Sched& S, const Epi& E) {
;     ...
;             PG8_WAIT_V(8); PG8_WAIT_L(0); PG8_BAR; PG8_MMA(1, 0, At, B0); PG8_MMA(1, 1, At, B1); PG8_BAR; PG8_SCHED;
;             PG8_LDB(B0, 1, 0); PG8_LDB(B1, 1, 1); PG8_SCHED; PG8_LDA(At, 1, 0); PG8_STAGE(PG8_SA(0, 1), a2 + hstepA, voffA);
;             PG8_WAIT_V(8); PG8_WAIT_L(0); PG8_BAR; PG8_MMA(0, 0, At, B0); PG8_MMA(0, 1, At, B1); PG8_BAR; PG8_SCHED;
	s_setprio 1
	s_waitcnt lgkmcnt(0)
	v_mfma_f32_16x16x32_bf16 v[62:65], v[136:139], v[180:183], v[62:65]
	v_mfma_f32_16x16x32_bf16 v[58:61], v[144:147], v[180:183], v[58:61]
	v_mfma_f32_16x16x32_bf16 v[46:49], v[136:139], v[188:191], v[46:49]
	v_mfma_f32_16x16x32_bf16 v[42:45], v[144:147], v[188:191], v[42:45]
	v_mfma_f32_16x16x32_bf16 v[30:33], v[136:139], v[196:199], v[30:33]
	v_mfma_f32_16x16x32_bf16 v[26:29], v[144:147], v[196:199], v[26:29]
	v_mfma_f32_16x16x32_bf16 v[14:17], v[136:139], v[204:207], v[14:17]
	v_mfma_f32_16x16x32_bf16 v[10:13], v[144:147], v[204:207], v[10:13]
	v_mfma_f32_16x16x32_bf16 v[62:65], v[140:143], v[184:187], v[62:65]
	v_mfma_f32_16x16x32_bf16 v[58:61], v[148:151], v[184:187], v[58:61]
	v_mfma_f32_16x16x32_bf16 v[46:49], v[140:143], v[192:195], v[46:49]
	v_mfma_f32_16x16x32_bf16 v[42:45], v[148:151], v[192:195], v[42:45]
	v_mfma_f32_16x16x32_bf16 v[30:33], v[140:143], v[200:203], v[30:33]
	v_mfma_f32_16x16x32_bf16 v[26:29], v[148:151], v[200:203], v[26:29]
	v_mfma_f32_16x16x32_bf16 v[14:17], v[140:143], v[208:211], v[14:17]
	v_mfma_f32_16x16x32_bf16 v[10:13], v[148:151], v[208:211], v[10:13]
	s_setprio 0
	s_setprio 1
	v_mfma_f32_16x16x32_bf16 v[54:57], v[152:155], v[180:183], v[54:57]
	v_mfma_f32_16x16x32_bf16 v[50:53], v[160:163], v[180:183], v[50:53]
	v_mfma_f32_16x16x32_bf16 v[38:41], v[152:155], v[188:191], v[38:41]
	v_mfma_f32_16x16x32_bf16 v[34:37], v[160:163], v[188:191], v[34:37]
	v_mfma_f32_16x16x32_bf16 v[22:25], v[152:155], v[196:199], v[22:25]
	v_mfma_f32_16x16x32_bf16 v[18:21], v[160:163], v[196:199], v[18:21]
	v_mfma_f32_16x16x32_bf16 v[6:9], v[152:155], v[204:207], v[6:9]
	v_mfma_f32_16x16x32_bf16 v[2:5], v[160:163], v[204:207], v[2:5]
	v_mfma_f32_16x16x32_bf16 v[54:57], v[156:159], v[184:187], v[54:57]
	v_mfma_f32_16x16x32_bf16 v[50:53], v[176:179], v[184:187], v[50:53]
	v_mfma_f32_16x16x32_bf16 v[38:41], v[156:159], v[192:195], v[38:41]
	v_mfma_f32_16x16x32_bf16 v[34:37], v[176:179], v[192:195], v[34:37]
	v_mfma_f32_16x16x32_bf16 v[22:25], v[156:159], v[200:203], v[22:25]
	v_mfma_f32_16x16x32_bf16 v[18:21], v[176:179], v[200:203], v[18:21]
	v_mfma_f32_16x16x32_bf16 v[6:9], v[156:159], v[208:211], v[6:9]
	v_mfma_f32_16x16x32_bf16 v[2:5], v[176:179], v[208:211], v[2:5]
	s_setprio 0
	s_barrier
	s_add_i32 s63, 0, 0x18000
	s_add_i32 s77, 0, 0x1c000
	v_add_u32_e32 v148, s63, v164
	v_add_u32_e32 v176, s77, v164
	ds_read_b128 v[136:139], v148
	ds_read_b128 v[140:143], v148 offset:1024
	ds_read_b128 v[144:147], v148 offset:256
	ds_read_b128 v[148:151], v148 offset:1280
	ds_read_b128 v[152:155], v176
	ds_read_b128 v[156:159], v176 offset:1024
	ds_read_b128 v[160:163], v176 offset:256
	ds_read_b128 v[176:179], v176 offset:1280
	s_add_u32 s44, s44, 0x40000
	s_addc_u32 s45, s45, 0
	s_mov_b32 m0, s38
	v_lshl_add_u64 v[216:217], s[44:45], 0, v[0:1]
	ds_read_b128 v[180:183], v165 offset:32768
	ds_read_b128 v[184:187], v165 offset:33792
	ds_read_b128 v[188:191], v165 offset:34816
	ds_read_b128 v[192:195], v165 offset:35840
	ds_read_b128 v[196:199], v165 offset:36864
	ds_read_b128 v[200:203], v165 offset:37888
	ds_read_b128 v[204:207], v165 offset:38912
	ds_read_b128 v[208:211], v165 offset:39936
	global_load_lds_dwordx4 v[216:217], off
	v_lshl_add_u64 v[216:217], s[44:45], 0, v[130:131]
	s_mov_b32 m0, s39
	s_nop 0
	global_load_lds_dwordx4 v[216:217], off
	s_waitcnt vmcnt(8)
	s_waitcnt lgkmcnt(0)
	s_barrier
	s_setprio 1
	s_waitcnt lgkmcnt(0)
	v_mfma_f32_16x16x32_bf16 v[126:129], v[136:139], v[180:183], v[126:129]
	v_mfma_f32_16x16x32_bf16 v[122:125], v[144:147], v[180:183], v[122:125]
	v_mfma_f32_16x16x32_bf16 v[110:113], v[136:139], v[188:191], v[110:113]
	v_mfma_f32_16x16x32_bf16 v[106:109], v[144:147], v[188:191], v[106:109]
	v_mfma_f32_16x16x32_bf16 v[94:97], v[136:139], v[196:199], v[94:97]
	v_mfma_f32_16x16x32_bf16 v[90:93], v[144:147], v[196:199], v[90:93]
	v_mfma_f32_16x16x32_bf16 v[78:81], v[136:139], v[204:207], v[78:81]
	v_mfma_f32_16x16x32_bf16 v[74:77], v[144:147], v[204:207], v[74:77]
	v_mfma_f32_16x16x32_bf16 v[126:129], v[140:143], v[184:187], v[126:129]
	v_mfma_f32_16x16x32_bf16 v[122:125], v[148:151], v[184:187], v[122:125]
	v_mfma_f32_16x16x32_bf16 v[110:113], v[140:143], v[192:195], v[110:113]
	v_mfma_f32_16x16x32_bf16 v[106:109], v[148:151], v[192:195], v[106:109]
	v_mfma_f32_16x16x32_bf16 v[94:97], v[140:143], v[200:203], v[94:97]
	v_mfma_f32_16x16x32_bf16 v[90:93], v[148:151], v[200:203], v[90:93]
	v_mfma_f32_16x16x32_bf16 v[78:81], v[140:143], v[208:211], v[78:81]
	v_mfma_f32_16x16x32_bf16 v[74:77], v[148:151], v[208:211], v[74:77]
	s_setprio 0
	s_setprio 1
	v_mfma_f32_16x16x32_bf16 v[118:121], v[152:155], v[180:183], v[118:121]
	v_mfma_f32_16x16x32_bf16 v[114:117], v[160:163], v[180:183], v[114:117]
	v_mfma_f32_16x16x32_bf16 v[102:105], v[152:155], v[188:191], v[102:105]
	v_mfma_f32_16x16x32_bf16 v[98:101], v[160:163], v[188:191], v[98:101]
	v_mfma_f32_16x16x32_bf16 v[86:89], v[152:155], v[196:199], v[86:89]
	v_mfma_f32_16x16x32_bf16 v[82:85], v[160:163], v[196:199], v[82:85]
	v_mfma_f32_16x16x32_bf16 v[70:73], v[152:155], v[204:207], v[70:73]
	v_mfma_f32_16x16x32_bf16 v[66:69], v[160:163], v[204:207], v[66:69]
	v_mfma_f32_16x16x32_bf16 v[118:121], v[156:159], v[184:187], v[118:121]
	v_mfma_f32_16x16x32_bf16 v[114:117], v[176:179], v[184:187], v[114:117]
	v_mfma_f32_16x16x32_bf16 v[102:105], v[156:159], v[192:195], v[102:105]
	v_mfma_f32_16x16x32_bf16 v[98:101], v[176:179], v[192:195], v[98:101]
	v_mfma_f32_16x16x32_bf16 v[86:89], v[156:159], v[200:203], v[86:89]
	v_mfma_f32_16x16x32_bf16 v[82:85], v[176:179], v[200:203], v[82:85]
	v_mfma_f32_16x16x32_bf16 v[70:73], v[156:159], v[208:211], v[70:73]
	v_mfma_f32_16x16x32_bf16 v[66:69], v[176:179], v[208:211], v[66:69]
	s_setprio 0
	s_barrier
; __device__ __forceinline__ int fresh_tid() { int t = threadIdx.x; asm volatile("" : "+v"(t)); return t; }
; #define PG8_STAGE(bufoff, gbase, voff) do { _Pragma("unroll") for (int _i = 0; _i < 2; ++_i) \
;         __builtin_amdgcn_global_load_lds((const unsigned*)((const char*)(gbase) + (voff)[_i]), (LAS unsigned*)(lds + (bufoff) + ldsw + _i * 8192), 16, 0, 0); } while (0)
; #define PG8_LDA(dst, b, h) do { _Pragma("unroll") for (int m = 0; m < 4; ++m) _Pragma("unroll") for (int k = 0; k < 2; ++k) dst[m][k] = *(const LAS bf16x8*)(lds + PG8_SA(b, h) + aoff + m * 2048 + k * 1024); } while (0)
; #define PG8_MMA(ai, bj, At, Bt) do { __builtin_amdgcn_s_setprio(1); _Pragma("unroll") for (int m = 0; m < 4; ++m) _Pragma("unroll") for (int n = 0; n < 2; ++n) _Pragma("unroll") for (int k = 0; k < 2; ++k) \
;         acc[ai][bj][m][n] = __builtin_amdgcn_mfma_f32_16x16x32_bf16(Bt[n][k], At[m][k], acc[ai][bj][m][n], 0, 0, 0); __builtin_amdgcn_s_setprio(0); } while (0)
; #define PG8_WAIT_V(n) asm volatile("s_waitcnt vmcnt(" #n ")" ::: "memory")
; #define PG8_WAIT_L(n) asm volatile("s_waitcnt lgkmcnt(" #n ")" ::: "memory")
; #define PG8_BAR __builtin_amdgcn_s_barrier()
; #define PG8_SCHED __builtin_amdgcn_sched_barrier(0)
;     __device__ __forceinline__ void operator()(f32x4 (&acc)[2][2][4][2], const Unit& u, int wr, int wc, int fr, int fq) const {
;         const int col0 = u.pn * BM + wc * 32 + 4 * fq;
; #pragma unroll
; template <class Epi, class Sched, int NSEG, int KK, int LDA, int LDB>
; __device__ __forceinline__ void gemm_phase(LAS unsigned char* lds, const Gemm g, const Sched& S, const Epi& E) {
;     ...
;             PG8_LDA(At, 1, 1); PG8_STAGE(PG8_SB(1, 0), b3, voffB); PG8_STAGE(PG8_SB(1, 1), b3 + hstepB, voffB); PG8_STAGE(PG8_SA(1, 0), a3, voffA);
;             PG8_WAIT_V(8); PG8_WAIT_L(0); PG8_BAR; PG8_MMA(1, 0, At, B0); PG8_MMA(1, 1, At, B1); PG8_BAR; PG8_SCHED;
;         }
;         if (wr == 0) PG8_BAR;
;         { const int t_e = fresh_tid(); int fr_e = t_e & 15, fq_e = (t_e >> 4) & 3; int wr_e = wr, wc_e = wc; asm volatile("" : "+s"(wr_e), "+s"(wc_e));
	s_add_i32 s44, s63, s23
	v_lshl_add_u64 v[166:167], v[166:167], 0, s[28:29]
	s_mov_b32 m0, s44
	ds_read_b128 v[180:183], v165 offset:49152
	ds_read_b128 v[184:187], v165 offset:50176
	ds_read_b128 v[188:191], v165 offset:51200
	ds_read_b128 v[192:195], v165 offset:52224
	ds_read_b128 v[196:199], v165 offset:53248
	ds_read_b128 v[200:203], v165 offset:54272
	ds_read_b128 v[204:207], v165 offset:55296
	ds_read_b128 v[208:211], v165 offset:56320
	global_load_lds_dwordx4 v[166:167], off
	s_add_i32 m0, s44, 0x2000
	s_add_u32 s10, s10, 0x40080
	v_lshl_add_u64 v[166:167], v[172:173], 0, s[28:29]
	s_addc_u32 s11, s11, 0
	s_add_i32 s44, s77, s23
	global_load_lds_dwordx4 v[166:167], off
	v_lshl_add_u64 v[166:167], s[10:11], 0, v[0:1]
	s_mov_b32 m0, s44
	s_nop 0
	global_load_lds_dwordx4 v[166:167], off
	v_lshl_add_u64 v[166:167], s[10:11], 0, v[130:131]
	s_add_i32 m0, s44, 0x2000
	s_nop 0
	global_load_lds_dwordx4 v[166:167], off
	v_lshl_add_u64 v[166:167], v[212:213], 0, s[28:29]
	s_mov_b32 m0, s57
	s_nop 0
	global_load_lds_dwordx4 v[166:167], off
	v_lshl_add_u64 v[166:167], v[214:215], 0, s[28:29]
	s_mov_b32 m0, s58
	s_nop 0
	global_load_lds_dwordx4 v[166:167], off
	s_waitcnt vmcnt(8)
	s_waitcnt lgkmcnt(0)
	s_barrier
	s_setprio 1
	s_waitcnt lgkmcnt(0)
	v_mfma_f32_16x16x32_bf16 v[62:65], v[136:139], v[180:183], v[62:65]
	v_mfma_f32_16x16x32_bf16 v[58:61], v[144:147], v[180:183], v[58:61]
	v_mfma_f32_16x16x32_bf16 v[46:49], v[136:139], v[188:191], v[46:49]
	v_mfma_f32_16x16x32_bf16 v[42:45], v[144:147], v[188:191], v[42:45]
	v_mfma_f32_16x16x32_bf16 v[30:33], v[136:139], v[196:199], v[30:33]
	v_mfma_f32_16x16x32_bf16 v[26:29], v[144:147], v[196:199], v[26:29]
	v_mfma_f32_16x16x32_bf16 v[14:17], v[136:139], v[204:207], v[14:17]
	v_mfma_f32_16x16x32_bf16 v[10:13], v[144:147], v[204:207], v[10:13]
	v_mfma_f32_16x16x32_bf16 v[62:65], v[140:143], v[184:187], v[62:65]
	v_mfma_f32_16x16x32_bf16 v[58:61], v[148:151], v[184:187], v[58:61]
	v_mfma_f32_16x16x32_bf16 v[46:49], v[140:143], v[192:195], v[46:49]
	v_mfma_f32_16x16x32_bf16 v[42:45], v[148:151], v[192:195], v[42:45]
	v_mfma_f32_16x16x32_bf16 v[30:33], v[140:143], v[200:203], v[30:33]
	v_mfma_f32_16x16x32_bf16 v[26:29], v[148:151], v[200:203], v[26:29]
	v_mfma_f32_16x16x32_bf16 v[14:17], v[140:143], v[208:211], v[14:17]
	v_mfma_f32_16x16x32_bf16 v[10:13], v[148:151], v[208:211], v[10:13]
	s_setprio 0
	s_setprio 1
	v_mfma_f32_16x16x32_bf16 v[54:57], v[152:155], v[180:183], v[54:57]
	v_mfma_f32_16x16x32_bf16 v[50:53], v[160:163], v[180:183], v[50:53]
	v_mfma_f32_16x16x32_bf16 v[38:41], v[152:155], v[188:191], v[38:41]
	v_mfma_f32_16x16x32_bf16 v[34:37], v[160:163], v[188:191], v[34:37]
	v_mfma_f32_16x16x32_bf16 v[22:25], v[152:155], v[196:199], v[22:25]
	v_mfma_f32_16x16x32_bf16 v[18:21], v[160:163], v[196:199], v[18:21]
	v_mfma_f32_16x16x32_bf16 v[6:9], v[152:155], v[204:207], v[6:9]
	v_mfma_f32_16x16x32_bf16 v[2:5], v[160:163], v[204:207], v[2:5]
	v_mfma_f32_16x16x32_bf16 v[54:57], v[156:159], v[184:187], v[54:57]
	v_mfma_f32_16x16x32_bf16 v[50:53], v[176:179], v[184:187], v[50:53]
	v_mfma_f32_16x16x32_bf16 v[38:41], v[156:159], v[192:195], v[38:41]
	v_mfma_f32_16x16x32_bf16 v[34:37], v[176:179], v[192:195], v[34:37]
	v_mfma_f32_16x16x32_bf16 v[22:25], v[156:159], v[200:203], v[22:25]
	v_mfma_f32_16x16x32_bf16 v[18:21], v[176:179], v[200:203], v[18:21]
	v_mfma_f32_16x16x32_bf16 v[6:9], v[156:159], v[208:211], v[6:9]
	v_mfma_f32_16x16x32_bf16 v[2:5], v[176:179], v[208:211], v[2:5]
	s_setprio 0
	s_barrier
	s_add_i32 s62, s62, 2
	s_add_u32 s42, s42, 0x100
	s_addc_u32 s43, s43, 0
	s_add_u32 s60, s60, 0x100
	s_addc_u32 s61, s61, 0
	s_cmp_gt_u32 s62, 13
	s_cbranch_scc0 .LBB0_985
	s_and_b64 vcc, exec, s[8:9]
	s_cbranch_vccz .LBB0_988
	s_barrier
.LBB0_988:
	v_mov_b32_e32 v136, v246
	s_mov_b32 s10, s22
	s_mov_b32 s54, s56
	s_lshl_b32 s11, s24, 8
	v_and_b32_e32 v137, 15, v136
	s_lshl_b32 s42, s54, 5
	v_bfe_u32 v138, v136, 4, 2
	s_add_i32 s42, s42, s11
	v_lshl_or_b32 v166, s10, 6, v137
	v_readlane_b32 s10, v255, 31
	v_lshl_or_b32 v136, v138, 3, s42
	v_readlane_b32 s11, v255, 32
	v_ashrrev_i32_e32 v137, 31, v136
	v_cmp_eq_u32_e64 s[42:43], 0, v138
	s_lshl_b32 s47, s25, 8
	v_cndmask_b32_e64 v138, 0, 1, s[10:11]
	s_ashr_i32 s55, s54, 31
	v_lshl_add_u64 v[136:137], v[136:137], 1, s[72:73]
	v_cmp_ne_u32_e64 s[44:45], 1, v138
	s_andn2_b64 vcc, exec, s[10:11]
	v_add_u32_e32 v138, s47, v166
	s_mov_b32 s94, s96
	s_cbranch_vccnz .LBB0_998
; __device__ __forceinline__ unsigned cvt_pk_bf16(float lo, float hi) { unsigned r; asm volatile("s_nop 1\n\tv_cvt_pk_bf16_f32 %0, %1, %2" : "=v"(r) : "v"(lo), "v"(hi)); return r; }
;     __device__ __forceinline__ void operator()(f32x4 (&acc)[2][2][4][2], const Unit& u, int wr, int wc, int fr, int fq) const {
;     ...
;         for (int ai = 0; ai < 2; ++ai) {
;             u32x2 bb[4][2][2];
;             if (!basef) {
; #pragma unroll
;                 for (int m = 0; m < 4; ++m) { const size_t off = (size_t)(u.pm * BM + ai * HALF + wr * 64 + m * 16 + fr) * ldc + col0;
; #pragma unroll
;                     for (int bj = 0; bj < 2; ++bj)
; #pragma unroll
;                         for (int n = 0; n < 2; ++n) bb[m][bj][n] = *(const u32x2*)(baseb + off + bj * HALF + n * 16); }
;             }
; #pragma unroll
;             for (int m = 0; m < 4; ++m) { const size_t row = (size_t)(u.pm * BM + ai * HALF + wr * 64 + m * 16 + fr); const size_t off = row * ldc + col0; float sq = 0.f;
; #pragma unroll
;                 for (int bj = 0; bj < 2; ++bj)
; #pragma unroll
;                     for (int n = 0; n < 2; ++n) { f32x4 bs;
;                         if (basef) bs = *(const f32x4*)(basef + off + bj * HALF + n * 16);
;                         else { const u32x2 b2 = bb[m][bj][n]; bs = (f32x4){bflo(b2.x), bfhi(b2.x), bflo(b2.y), bfhi(b2.y)}; }
;                         const f32x4 v = bs + acc[ai][bj][m][n];
;                         if (out) *(f32x4*)(out + off + bj * HALF + n * 16) = v;
;                         if (hb) { sq += (v.x * v.x + v.y * v.y) + (v.z * v.z + v.w * v.w); *(u32x2*)(hb + off + bj * HALF + n * 16) = (u32x2){cvt_pk_bf16(v.x, v.y), cvt_pk_bf16(v.z, v.w)}; } }
;                 if (hb) { sq += __shfl_xor(sq, 16); sq += __shfl_xor(sq, 32); if (fq == 0) ssq[((size_t)u.pn * T + row) * 4 + wc] = sq; } }
	v_mov_b32_e32 v186, v138
	v_ashrrev_i32_e32 v187, 31, v186
	v_lshlrev_b64 v[194:195], 11, v[186:187]
	v_lshl_add_u64 v[194:195], v[136:137], 0, v[194:195]
	global_load_dwordx4 v[204:207], v[194:195], off
	global_load_dwordx4 v[208:211], v[194:195], off offset:256
	v_add_u32_e32 v188, 16, v138
	v_ashrrev_i32_e32 v189, 31, v188
	v_lshlrev_b64 v[196:197], 11, v[188:189]
	v_lshl_add_u64 v[196:197], v[136:137], 0, v[196:197]
	global_load_dwordx4 v[212:215], v[196:197], off
	global_load_dwordx4 v[216:219], v[196:197], off offset:256
	v_add_u32_e32 v190, 32, v138
	v_ashrrev_i32_e32 v191, 31, v190
	v_lshlrev_b64 v[198:199], 11, v[190:191]
	v_lshl_add_u64 v[198:199], v[136:137], 0, v[198:199]
	global_load_dwordx4 v[220:223], v[198:199], off
	global_load_dwordx4 v[224:227], v[198:199], off offset:256
	v_add_u32_e32 v192, 48, v138
	v_ashrrev_i32_e32 v193, 31, v192
	v_lshlrev_b64 v[200:201], 11, v[192:193]
	v_lshl_add_u64 v[200:201], v[136:137], 0, v[200:201]
	global_load_dwordx4 v[228:231], v[200:201], off
	global_load_dwordx4 v[232:235], v[200:201], off offset:256
	v_xor_b32_e32 v244, 16, v249
	v_xor_b32_e32 v245, 32, v249
	v_lshlrev_b32_e32 v244, 2, v244
	v_lshlrev_b32_e32 v245, 2, v245
	s_waitcnt vmcnt(6)
	v_lshlrev_b32_e32 v202, 16, v204
	v_and_b32_e32 v203, 0xffff0000, v204
	v_pk_add_f32 v[126:127], v[126:127], v[202:203]
	v_mul_f32_e32 v236, v126, v126
	v_mul_f32_e32 v240, v127, v127
	v_lshlrev_b32_e32 v202, 16, v205
	v_and_b32_e32 v203, 0xffff0000, v205
	v_pk_add_f32 v[128:129], v[128:129], v[202:203]
	v_fmac_f32_e32 v236, v128, v128
	v_fmac_f32_e32 v240, v129, v129
	v_lshlrev_b32_e32 v202, 16, v206
	v_and_b32_e32 v203, 0xffff0000, v206
	v_pk_add_f32 v[122:123], v[122:123], v[202:203]
	v_fmac_f32_e32 v236, v122, v122
	v_fmac_f32_e32 v240, v123, v123
	v_lshlrev_b32_e32 v202, 16, v207
	v_and_b32_e32 v203, 0xffff0000, v207
	v_pk_add_f32 v[124:125], v[124:125], v[202:203]
	v_fmac_f32_e32 v236, v124, v124
	v_fmac_f32_e32 v240, v125, v125
	v_cvt_pk_bf16_f32 v204, v126, v127
	v_cvt_pk_bf16_f32 v205, v128, v129
	v_cvt_pk_bf16_f32 v206, v122, v123
	v_cvt_pk_bf16_f32 v207, v124, v125
	global_store_dwordx4 v[194:195], v[204:207], off
	v_lshlrev_b32_e32 v202, 16, v208
	v_and_b32_e32 v203, 0xffff0000, v208
	v_pk_add_f32 v[118:119], v[118:119], v[202:203]
	v_fmac_f32_e32 v236, v118, v118
	v_fmac_f32_e32 v240, v119, v119
	v_lshlrev_b32_e32 v202, 16, v209
	v_and_b32_e32 v203, 0xffff0000, v209
	v_pk_add_f32 v[120:121], v[120:121], v[202:203]
	v_fmac_f32_e32 v236, v120, v120
	v_fmac_f32_e32 v240, v121, v121
	v_lshlrev_b32_e32 v202, 16, v210
	v_and_b32_e32 v203, 0xffff0000, v210
	v_pk_add_f32 v[114:115], v[114:115], v[202:203]
	v_fmac_f32_e32 v236, v114, v114
	v_fmac_f32_e32 v240, v115, v115
	v_lshlrev_b32_e32 v202, 16, v211
	v_and_b32_e32 v203, 0xffff0000, v211
	v_pk_add_f32 v[116:117], v[116:117], v[202:203]
	v_fmac_f32_e32 v236, v116, v116
	v_fmac_f32_e32 v240, v117, v117
	v_cvt_pk_bf16_f32 v208, v118, v119
	v_cvt_pk_bf16_f32 v209, v120, v121
	v_cvt_pk_bf16_f32 v210, v114, v115
	v_cvt_pk_bf16_f32 v211, v116, v117
	global_store_dwordx4 v[194:195], v[208:211], off offset:256
	v_add_f32_e32 v236, v236, v240
	s_waitcnt vmcnt(6)
	v_lshlrev_b32_e32 v202, 16, v212
	v_and_b32_e32 v203, 0xffff0000, v212
	v_pk_add_f32 v[110:111], v[110:111], v[202:203]
	v_mul_f32_e32 v237, v110, v110
	v_mul_f32_e32 v241, v111, v111
	v_lshlrev_b32_e32 v202, 16, v213
	v_and_b32_e32 v203, 0xffff0000, v213
	v_pk_add_f32 v[112:113], v[112:113], v[202:203]
	v_fmac_f32_e32 v237, v112, v112
	v_fmac_f32_e32 v241, v113, v113
	v_lshlrev_b32_e32 v202, 16, v214
	v_and_b32_e32 v203, 0xffff0000, v214
	v_pk_add_f32 v[106:107], v[106:107], v[202:203]
	v_fmac_f32_e32 v237, v106, v106
	v_fmac_f32_e32 v241, v107, v107
	v_lshlrev_b32_e32 v202, 16, v215
	v_and_b32_e32 v203, 0xffff0000, v215
	v_pk_add_f32 v[108:109], v[108:109], v[202:203]
	v_fmac_f32_e32 v237, v108, v108
	v_fmac_f32_e32 v241, v109, v109
	v_cvt_pk_bf16_f32 v212, v110, v111
	v_cvt_pk_bf16_f32 v213, v112, v113
	v_cvt_pk_bf16_f32 v214, v106, v107
	v_cvt_pk_bf16_f32 v215, v108, v109
	global_store_dwordx4 v[196:197], v[212:215], off
	v_lshlrev_b32_e32 v202, 16, v216
	v_and_b32_e32 v203, 0xffff0000, v216
	v_pk_add_f32 v[102:103], v[102:103], v[202:203]
	v_fmac_f32_e32 v237, v102, v102
	v_fmac_f32_e32 v241, v103, v103
	v_lshlrev_b32_e32 v202, 16, v217
	v_and_b32_e32 v203, 0xffff0000, v217
	v_pk_add_f32 v[104:105], v[104:105], v[202:203]
	v_fmac_f32_e32 v237, v104, v104
	v_fmac_f32_e32 v241, v105, v105
	v_lshlrev_b32_e32 v202, 16, v218
	v_and_b32_e32 v203, 0xffff0000, v218
	v_pk_add_f32 v[98:99], v[98:99], v[202:203]
	v_fmac_f32_e32 v237, v98, v98
	v_fmac_f32_e32 v241, v99, v99
	v_lshlrev_b32_e32 v202, 16, v219
	v_and_b32_e32 v203, 0xffff0000, v219
	v_pk_add_f32 v[100:101], v[100:101], v[202:203]
	v_fmac_f32_e32 v237, v100, v100
	v_fmac_f32_e32 v241, v101, v101
	v_cvt_pk_bf16_f32 v216, v102, v103
	v_cvt_pk_bf16_f32 v217, v104, v105
	v_cvt_pk_bf16_f32 v218, v98, v99
	v_cvt_pk_bf16_f32 v219, v100, v101
	global_store_dwordx4 v[196:197], v[216:219], off offset:256
	v_add_f32_e32 v237, v237, v241
	s_waitcnt vmcnt(6)
; __device__ __forceinline__ unsigned cvt_pk_bf16(float lo, float hi) { unsigned r; asm volatile("s_nop 1\n\tv_cvt_pk_bf16_f32 %0, %1, %2" : "=v"(r) : "v"(lo), "v"(hi)); return r; }
;     __device__ __forceinline__ void operator()(f32x4 (&acc)[2][2][4][2], const Unit& u, int wr, int wc, int fr, int fq) const {
;     ...
;             for (int m = 0; m < 4; ++m) { const size_t row = (size_t)(u.pm * BM + ai * HALF + wr * 64 + m * 16 + fr); const size_t off = row * ldc + col0; float sq = 0.f;
; #pragma unroll
;                 for (int bj = 0; bj < 2; ++bj)
; #pragma unroll
;                     for (int n = 0; n < 2; ++n) { f32x4 bs;
;                         if (basef) bs = *(const f32x4*)(basef + off + bj * HALF + n * 16);
;                         else { const u32x2 b2 = bb[m][bj][n]; bs = (f32x4){bflo(b2.x), bfhi(b2.x), bflo(b2.y), bfhi(b2.y)}; }
;                         const f32x4 v = bs + acc[ai][bj][m][n];
;                         if (out) *(f32x4*)(out + off + bj * HALF + n * 16) = v;
;                         if (hb) { sq += (v.x * v.x + v.y * v.y) + (v.z * v.z + v.w * v.w); *(u32x2*)(hb + off + bj * HALF + n * 16) = (u32x2){cvt_pk_bf16(v.x, v.y), cvt_pk_bf16(v.z, v.w)}; } }
;                 if (hb) { sq += __shfl_xor(sq, 16); sq += __shfl_xor(sq, 32); if (fq == 0) ssq[((size_t)u.pn * T + row) * 4 + wc] = sq; } }
	v_lshlrev_b32_e32 v202, 16, v220
	v_and_b32_e32 v203, 0xffff0000, v220
	v_pk_add_f32 v[94:95], v[94:95], v[202:203]
	v_mul_f32_e32 v238, v94, v94
	v_mul_f32_e32 v242, v95, v95
	v_lshlrev_b32_e32 v202, 16, v221
	v_and_b32_e32 v203, 0xffff0000, v221
	v_pk_add_f32 v[96:97], v[96:97], v[202:203]
	v_fmac_f32_e32 v238, v96, v96
	v_fmac_f32_e32 v242, v97, v97
	v_lshlrev_b32_e32 v202, 16, v222
	v_and_b32_e32 v203, 0xffff0000, v222
	v_pk_add_f32 v[90:91], v[90:91], v[202:203]
	v_fmac_f32_e32 v238, v90, v90
	v_fmac_f32_e32 v242, v91, v91
	v_lshlrev_b32_e32 v202, 16, v223
	v_and_b32_e32 v203, 0xffff0000, v223
	v_pk_add_f32 v[92:93], v[92:93], v[202:203]
	v_fmac_f32_e32 v238, v92, v92
	v_fmac_f32_e32 v242, v93, v93
	v_cvt_pk_bf16_f32 v220, v94, v95
	v_cvt_pk_bf16_f32 v221, v96, v97
	v_cvt_pk_bf16_f32 v222, v90, v91
	v_cvt_pk_bf16_f32 v223, v92, v93
	global_store_dwordx4 v[198:199], v[220:223], off
	v_lshlrev_b32_e32 v202, 16, v224
	v_and_b32_e32 v203, 0xffff0000, v224
	v_pk_add_f32 v[86:87], v[86:87], v[202:203]
	v_fmac_f32_e32 v238, v86, v86
	v_fmac_f32_e32 v242, v87, v87
	v_lshlrev_b32_e32 v202, 16, v225
	v_and_b32_e32 v203, 0xffff0000, v225
	v_pk_add_f32 v[88:89], v[88:89], v[202:203]
	v_fmac_f32_e32 v238, v88, v88
	v_fmac_f32_e32 v242, v89, v89
	v_lshlrev_b32_e32 v202, 16, v226
	v_and_b32_e32 v203, 0xffff0000, v226
	v_pk_add_f32 v[82:83], v[82:83], v[202:203]
	v_fmac_f32_e32 v238, v82, v82
	v_fmac_f32_e32 v242, v83, v83
	v_lshlrev_b32_e32 v202, 16, v227
	v_and_b32_e32 v203, 0xffff0000, v227
	v_pk_add_f32 v[84:85], v[84:85], v[202:203]
	v_fmac_f32_e32 v238, v84, v84
	v_fmac_f32_e32 v242, v85, v85
	v_cvt_pk_bf16_f32 v224, v86, v87
	v_cvt_pk_bf16_f32 v225, v88, v89
	v_cvt_pk_bf16_f32 v226, v82, v83
	v_cvt_pk_bf16_f32 v227, v84, v85
	global_store_dwordx4 v[198:199], v[224:227], off offset:256
	v_add_f32_e32 v238, v238, v242
	s_waitcnt vmcnt(6)
	v_lshlrev_b32_e32 v202, 16, v228
	v_and_b32_e32 v203, 0xffff0000, v228
	v_pk_add_f32 v[78:79], v[78:79], v[202:203]
	v_mul_f32_e32 v239, v78, v78
	v_mul_f32_e32 v243, v79, v79
	v_lshlrev_b32_e32 v202, 16, v229
	v_and_b32_e32 v203, 0xffff0000, v229
	v_pk_add_f32 v[80:81], v[80:81], v[202:203]
	v_fmac_f32_e32 v239, v80, v80
	v_fmac_f32_e32 v243, v81, v81
	v_lshlrev_b32_e32 v202, 16, v230
	v_and_b32_e32 v203, 0xffff0000, v230
	v_pk_add_f32 v[74:75], v[74:75], v[202:203]
	v_fmac_f32_e32 v239, v74, v74
	v_fmac_f32_e32 v243, v75, v75
	v_lshlrev_b32_e32 v202, 16, v231
	v_and_b32_e32 v203, 0xffff0000, v231
	v_pk_add_f32 v[76:77], v[76:77], v[202:203]
	v_fmac_f32_e32 v239, v76, v76
	v_fmac_f32_e32 v243, v77, v77
	v_cvt_pk_bf16_f32 v228, v78, v79
	v_cvt_pk_bf16_f32 v229, v80, v81
	v_cvt_pk_bf16_f32 v230, v74, v75
	v_cvt_pk_bf16_f32 v231, v76, v77
	global_store_dwordx4 v[200:201], v[228:231], off
	v_lshlrev_b32_e32 v202, 16, v232
	v_and_b32_e32 v203, 0xffff0000, v232
	v_pk_add_f32 v[70:71], v[70:71], v[202:203]
	v_fmac_f32_e32 v239, v70, v70
	v_fmac_f32_e32 v243, v71, v71
	v_lshlrev_b32_e32 v202, 16, v233
	v_and_b32_e32 v203, 0xffff0000, v233
	v_pk_add_f32 v[72:73], v[72:73], v[202:203]
	v_fmac_f32_e32 v239, v72, v72
	v_fmac_f32_e32 v243, v73, v73
	v_lshlrev_b32_e32 v202, 16, v234
	v_and_b32_e32 v203, 0xffff0000, v234
	v_pk_add_f32 v[66:67], v[66:67], v[202:203]
	v_fmac_f32_e32 v239, v66, v66
	v_fmac_f32_e32 v243, v67, v67
	v_lshlrev_b32_e32 v202, 16, v235
	v_and_b32_e32 v203, 0xffff0000, v235
	v_pk_add_f32 v[68:69], v[68:69], v[202:203]
	v_fmac_f32_e32 v239, v68, v68
	v_fmac_f32_e32 v243, v69, v69
	v_cvt_pk_bf16_f32 v232, v70, v71
	v_cvt_pk_bf16_f32 v233, v72, v73
	v_cvt_pk_bf16_f32 v234, v66, v67
	v_cvt_pk_bf16_f32 v235, v68, v69
	global_store_dwordx4 v[200:201], v[232:235], off offset:256
	v_add_f32_e32 v239, v239, v243
	ds_bpermute_b32 v240, v244, v236
	ds_bpermute_b32 v241, v244, v237
	ds_bpermute_b32 v242, v244, v238
	ds_bpermute_b32 v243, v244, v239
	s_ashr_i32 s25, s24, 31
	s_lshl_b64 s[60:61], s[24:25], 19
	s_add_u32 s60, s70, s60
	s_addc_u32 s61, s71, s61
	s_waitcnt lgkmcnt(0)
	v_add_f32_e32 v236, v236, v240
	v_add_f32_e32 v237, v237, v241
	v_add_f32_e32 v238, v238, v242
	v_add_f32_e32 v239, v239, v243
	ds_bpermute_b32 v240, v245, v236
	ds_bpermute_b32 v241, v245, v237
	ds_bpermute_b32 v242, v245, v238
	ds_bpermute_b32 v243, v245, v239
	v_lshl_add_u64 v[204:205], v[186:187], 4, s[60:61]
	v_lshl_add_u64 v[204:205], s[54:55], 2, v[204:205]
	v_lshl_add_u64 v[212:213], v[188:189], 4, s[60:61]
	v_lshl_add_u64 v[212:213], s[54:55], 2, v[212:213]
	v_lshl_add_u64 v[220:221], v[190:191], 4, s[60:61]
	v_lshl_add_u64 v[220:221], s[54:55], 2, v[220:221]
	v_lshl_add_u64 v[228:229], v[192:193], 4, s[60:61]
	v_lshl_add_u64 v[228:229], s[54:55], 2, v[228:229]
	s_waitcnt lgkmcnt(0)
	v_add_f32_e32 v236, v236, v240
	v_add_f32_e32 v237, v237, v241
	v_add_f32_e32 v238, v238, v242
	v_add_f32_e32 v239, v239, v243
	s_and_saveexec_b64 s[10:11], s[42:43]
	global_store_dword v[204:205], v236, off
	global_store_dword v[212:213], v237, off
	global_store_dword v[220:221], v238, off
	global_store_dword v[228:229], v239, off
	s_or_b64 exec, exec, s[10:11]
; __device__ __forceinline__ unsigned cvt_pk_bf16(float lo, float hi) { unsigned r; asm volatile("s_nop 1\n\tv_cvt_pk_bf16_f32 %0, %1, %2" : "=v"(r) : "v"(lo), "v"(hi)); return r; }
;     __device__ __forceinline__ void operator()(f32x4 (&acc)[2][2][4][2], const Unit& u, int wr, int wc, int fr, int fq) const {
;     ...
;         for (int ai = 0; ai < 2; ++ai) {
;             u32x2 bb[4][2][2];
;             if (!basef) {
; #pragma unroll
;                 for (int m = 0; m < 4; ++m) { const size_t off = (size_t)(u.pm * BM + ai * HALF + wr * 64 + m * 16 + fr) * ldc + col0;
; #pragma unroll
;                     for (int bj = 0; bj < 2; ++bj)
; #pragma unroll
;                         for (int n = 0; n < 2; ++n) bb[m][bj][n] = *(const u32x2*)(baseb + off + bj * HALF + n * 16); }
;             }
; #pragma unroll
;             for (int m = 0; m < 4; ++m) { const size_t row = (size_t)(u.pm * BM + ai * HALF + wr * 64 + m * 16 + fr); const size_t off = row * ldc + col0; float sq = 0.f;
; #pragma unroll
;                 for (int bj = 0; bj < 2; ++bj)
; #pragma unroll
;                     for (int n = 0; n < 2; ++n) { f32x4 bs;
;                         if (basef) bs = *(const f32x4*)(basef + off + bj * HALF + n * 16);
;                         else { const u32x2 b2 = bb[m][bj][n]; bs = (f32x4){bflo(b2.x), bfhi(b2.x), bflo(b2.y), bfhi(b2.y)}; }
;                         const f32x4 v = bs + acc[ai][bj][m][n];
;                         if (out) *(f32x4*)(out + off + bj * HALF + n * 16) = v;
;                         if (hb) { sq += (v.x * v.x + v.y * v.y) + (v.z * v.z + v.w * v.w); *(u32x2*)(hb + off + bj * HALF + n * 16) = (u32x2){cvt_pk_bf16(v.x, v.y), cvt_pk_bf16(v.z, v.w)}; } }
;                 if (hb) { sq += __shfl_xor(sq, 16); sq += __shfl_xor(sq, 32); if (fq == 0) ssq[((size_t)u.pn * T + row) * 4 + wc] = sq; } }
.LBB0_998:
	s_and_b64 vcc, exec, s[44:45]
	s_cbranch_vccnz .LBB0_1008
	v_add_u32_e32 v186, 128, v138
	v_ashrrev_i32_e32 v187, 31, v186
	v_lshlrev_b64 v[194:195], 11, v[186:187]
	v_lshl_add_u64 v[194:195], v[136:137], 0, v[194:195]
	global_load_dwordx4 v[204:207], v[194:195], off
	global_load_dwordx4 v[208:211], v[194:195], off offset:256
	v_add_u32_e32 v188, 144, v138
	v_ashrrev_i32_e32 v189, 31, v188
	v_lshlrev_b64 v[196:197], 11, v[188:189]
	v_lshl_add_u64 v[196:197], v[136:137], 0, v[196:197]
	global_load_dwordx4 v[212:215], v[196:197], off
	global_load_dwordx4 v[216:219], v[196:197], off offset:256
	v_add_u32_e32 v190, 160, v138
	v_ashrrev_i32_e32 v191, 31, v190
	v_lshlrev_b64 v[198:199], 11, v[190:191]
	v_lshl_add_u64 v[198:199], v[136:137], 0, v[198:199]
	global_load_dwordx4 v[220:223], v[198:199], off
	global_load_dwordx4 v[224:227], v[198:199], off offset:256
	v_add_u32_e32 v192, 176, v138
	v_ashrrev_i32_e32 v193, 31, v192
	v_lshlrev_b64 v[200:201], 11, v[192:193]
	v_lshl_add_u64 v[200:201], v[136:137], 0, v[200:201]
	global_load_dwordx4 v[228:231], v[200:201], off
	global_load_dwordx4 v[232:235], v[200:201], off offset:256
	v_xor_b32_e32 v244, 16, v249
	v_xor_b32_e32 v245, 32, v249
	v_lshlrev_b32_e32 v244, 2, v244
	v_lshlrev_b32_e32 v245, 2, v245
	s_waitcnt vmcnt(6)
	v_lshlrev_b32_e32 v202, 16, v204
	v_and_b32_e32 v203, 0xffff0000, v204
	v_pk_add_f32 v[62:63], v[62:63], v[202:203]
	v_mul_f32_e32 v236, v62, v62
	v_mul_f32_e32 v240, v63, v63
	v_lshlrev_b32_e32 v202, 16, v205
	v_and_b32_e32 v203, 0xffff0000, v205
	v_pk_add_f32 v[64:65], v[64:65], v[202:203]
	v_fmac_f32_e32 v236, v64, v64
	v_fmac_f32_e32 v240, v65, v65
	v_lshlrev_b32_e32 v202, 16, v206
	v_and_b32_e32 v203, 0xffff0000, v206
	v_pk_add_f32 v[58:59], v[58:59], v[202:203]
	v_fmac_f32_e32 v236, v58, v58
	v_fmac_f32_e32 v240, v59, v59
	v_lshlrev_b32_e32 v202, 16, v207
	v_and_b32_e32 v203, 0xffff0000, v207
	v_pk_add_f32 v[60:61], v[60:61], v[202:203]
	v_fmac_f32_e32 v236, v60, v60
	v_fmac_f32_e32 v240, v61, v61
	v_cvt_pk_bf16_f32 v204, v62, v63
	v_cvt_pk_bf16_f32 v205, v64, v65
	v_cvt_pk_bf16_f32 v206, v58, v59
	v_cvt_pk_bf16_f32 v207, v60, v61
	global_store_dwordx4 v[194:195], v[204:207], off
	v_lshlrev_b32_e32 v202, 16, v208
	v_and_b32_e32 v203, 0xffff0000, v208
	v_pk_add_f32 v[54:55], v[54:55], v[202:203]
	v_fmac_f32_e32 v236, v54, v54
	v_fmac_f32_e32 v240, v55, v55
	v_lshlrev_b32_e32 v202, 16, v209
	v_and_b32_e32 v203, 0xffff0000, v209
	v_pk_add_f32 v[56:57], v[56:57], v[202:203]
	v_fmac_f32_e32 v236, v56, v56
	v_fmac_f32_e32 v240, v57, v57
	v_lshlrev_b32_e32 v202, 16, v210
	v_and_b32_e32 v203, 0xffff0000, v210
	v_pk_add_f32 v[50:51], v[50:51], v[202:203]
	v_fmac_f32_e32 v236, v50, v50
	v_fmac_f32_e32 v240, v51, v51
	v_lshlrev_b32_e32 v202, 16, v211
	v_and_b32_e32 v203, 0xffff0000, v211
	v_pk_add_f32 v[52:53], v[52:53], v[202:203]
	v_fmac_f32_e32 v236, v52, v52
	v_fmac_f32_e32 v240, v53, v53
	v_cvt_pk_bf16_f32 v208, v54, v55
	v_cvt_pk_bf16_f32 v209, v56, v57
	v_cvt_pk_bf16_f32 v210, v50, v51
	v_cvt_pk_bf16_f32 v211, v52, v53
	global_store_dwordx4 v[194:195], v[208:211], off offset:256
	v_add_f32_e32 v236, v236, v240
	s_waitcnt vmcnt(6)
	v_lshlrev_b32_e32 v202, 16, v212
	v_and_b32_e32 v203, 0xffff0000, v212
	v_pk_add_f32 v[46:47], v[46:47], v[202:203]
	v_mul_f32_e32 v237, v46, v46
	v_mul_f32_e32 v241, v47, v47
	v_lshlrev_b32_e32 v202, 16, v213
	v_and_b32_e32 v203, 0xffff0000, v213
	v_pk_add_f32 v[48:49], v[48:49], v[202:203]
	v_fmac_f32_e32 v237, v48, v48
	v_fmac_f32_e32 v241, v49, v49
	v_lshlrev_b32_e32 v202, 16, v214
	v_and_b32_e32 v203, 0xffff0000, v214
	v_pk_add_f32 v[42:43], v[42:43], v[202:203]
	v_fmac_f32_e32 v237, v42, v42
	v_fmac_f32_e32 v241, v43, v43
	v_lshlrev_b32_e32 v202, 16, v215
	v_and_b32_e32 v203, 0xffff0000, v215
	v_pk_add_f32 v[44:45], v[44:45], v[202:203]
	v_fmac_f32_e32 v237, v44, v44
	v_fmac_f32_e32 v241, v45, v45
	v_cvt_pk_bf16_f32 v212, v46, v47
	v_cvt_pk_bf16_f32 v213, v48, v49
	v_cvt_pk_bf16_f32 v214, v42, v43
	v_cvt_pk_bf16_f32 v215, v44, v45
	global_store_dwordx4 v[196:197], v[212:215], off
	v_lshlrev_b32_e32 v202, 16, v216
	v_and_b32_e32 v203, 0xffff0000, v216
	v_pk_add_f32 v[38:39], v[38:39], v[202:203]
	v_fmac_f32_e32 v237, v38, v38
	v_fmac_f32_e32 v241, v39, v39
	v_lshlrev_b32_e32 v202, 16, v217
	v_and_b32_e32 v203, 0xffff0000, v217
	v_pk_add_f32 v[40:41], v[40:41], v[202:203]
	v_fmac_f32_e32 v237, v40, v40
	v_fmac_f32_e32 v241, v41, v41
	v_lshlrev_b32_e32 v202, 16, v218
	v_and_b32_e32 v203, 0xffff0000, v218
	v_pk_add_f32 v[34:35], v[34:35], v[202:203]
	v_fmac_f32_e32 v237, v34, v34
	v_fmac_f32_e32 v241, v35, v35
	v_lshlrev_b32_e32 v202, 16, v219
	v_and_b32_e32 v203, 0xffff0000, v219
	v_pk_add_f32 v[36:37], v[36:37], v[202:203]
	v_fmac_f32_e32 v237, v36, v36
	v_fmac_f32_e32 v241, v37, v37
	v_cvt_pk_bf16_f32 v216, v38, v39
	v_cvt_pk_bf16_f32 v217, v40, v41
	v_cvt_pk_bf16_f32 v218, v34, v35
	v_cvt_pk_bf16_f32 v219, v36, v37
	global_store_dwordx4 v[196:197], v[216:219], off offset:256
	v_add_f32_e32 v237, v237, v241
	s_waitcnt vmcnt(6)
; __device__ __forceinline__ unsigned cvt_pk_bf16(float lo, float hi) { unsigned r; asm volatile("s_nop 1\n\tv_cvt_pk_bf16_f32 %0, %1, %2" : "=v"(r) : "v"(lo), "v"(hi)); return r; }
;     __device__ __forceinline__ void operator()(f32x4 (&acc)[2][2][4][2], const Unit& u, int wr, int wc, int fr, int fq) const {
;     ...
;             for (int m = 0; m < 4; ++m) { const size_t row = (size_t)(u.pm * BM + ai * HALF + wr * 64 + m * 16 + fr); const size_t off = row * ldc + col0; float sq = 0.f;
; #pragma unroll
;                 for (int bj = 0; bj < 2; ++bj)
; #pragma unroll
;                     for (int n = 0; n < 2; ++n) { f32x4 bs;
;                         if (basef) bs = *(const f32x4*)(basef + off + bj * HALF + n * 16);
;                         else { const u32x2 b2 = bb[m][bj][n]; bs = (f32x4){bflo(b2.x), bfhi(b2.x), bflo(b2.y), bfhi(b2.y)}; }
;                         const f32x4 v = bs + acc[ai][bj][m][n];
;                         if (out) *(f32x4*)(out + off + bj * HALF + n * 16) = v;
;                         if (hb) { sq += (v.x * v.x + v.y * v.y) + (v.z * v.z + v.w * v.w); *(u32x2*)(hb + off + bj * HALF + n * 16) = (u32x2){cvt_pk_bf16(v.x, v.y), cvt_pk_bf16(v.z, v.w)}; } }
;                 if (hb) { sq += __shfl_xor(sq, 16); sq += __shfl_xor(sq, 32); if (fq == 0) ssq[((size_t)u.pn * T + row) * 4 + wc] = sq; } }
	v_lshlrev_b32_e32 v202, 16, v220
	v_and_b32_e32 v203, 0xffff0000, v220
	v_pk_add_f32 v[30:31], v[30:31], v[202:203]
	v_mul_f32_e32 v238, v30, v30
	v_mul_f32_e32 v242, v31, v31
	v_lshlrev_b32_e32 v202, 16, v221
	v_and_b32_e32 v203, 0xffff0000, v221
	v_pk_add_f32 v[32:33], v[32:33], v[202:203]
	v_fmac_f32_e32 v238, v32, v32
	v_fmac_f32_e32 v242, v33, v33
	v_lshlrev_b32_e32 v202, 16, v222
	v_and_b32_e32 v203, 0xffff0000, v222
	v_pk_add_f32 v[26:27], v[26:27], v[202:203]
	v_fmac_f32_e32 v238, v26, v26
	v_fmac_f32_e32 v242, v27, v27
	v_lshlrev_b32_e32 v202, 16, v223
	v_and_b32_e32 v203, 0xffff0000, v223
	v_pk_add_f32 v[28:29], v[28:29], v[202:203]
	v_fmac_f32_e32 v238, v28, v28
	v_fmac_f32_e32 v242, v29, v29
	v_cvt_pk_bf16_f32 v220, v30, v31
	v_cvt_pk_bf16_f32 v221, v32, v33
	v_cvt_pk_bf16_f32 v222, v26, v27
	v_cvt_pk_bf16_f32 v223, v28, v29
	global_store_dwordx4 v[198:199], v[220:223], off
	v_lshlrev_b32_e32 v202, 16, v224
	v_and_b32_e32 v203, 0xffff0000, v224
	v_pk_add_f32 v[22:23], v[22:23], v[202:203]
	v_fmac_f32_e32 v238, v22, v22
	v_fmac_f32_e32 v242, v23, v23
	v_lshlrev_b32_e32 v202, 16, v225
	v_and_b32_e32 v203, 0xffff0000, v225
	v_pk_add_f32 v[24:25], v[24:25], v[202:203]
	v_fmac_f32_e32 v238, v24, v24
	v_fmac_f32_e32 v242, v25, v25
	v_lshlrev_b32_e32 v202, 16, v226
	v_and_b32_e32 v203, 0xffff0000, v226
	v_pk_add_f32 v[18:19], v[18:19], v[202:203]
	v_fmac_f32_e32 v238, v18, v18
	v_fmac_f32_e32 v242, v19, v19
	v_lshlrev_b32_e32 v202, 16, v227
	v_and_b32_e32 v203, 0xffff0000, v227
	v_pk_add_f32 v[20:21], v[20:21], v[202:203]
	v_fmac_f32_e32 v238, v20, v20
	v_fmac_f32_e32 v242, v21, v21
	v_cvt_pk_bf16_f32 v224, v22, v23
	v_cvt_pk_bf16_f32 v225, v24, v25
	v_cvt_pk_bf16_f32 v226, v18, v19
	v_cvt_pk_bf16_f32 v227, v20, v21
	global_store_dwordx4 v[198:199], v[224:227], off offset:256
	v_add_f32_e32 v238, v238, v242
	s_waitcnt vmcnt(6)
	v_lshlrev_b32_e32 v202, 16, v228
	v_and_b32_e32 v203, 0xffff0000, v228
	v_pk_add_f32 v[14:15], v[14:15], v[202:203]
	v_mul_f32_e32 v239, v14, v14
	v_mul_f32_e32 v243, v15, v15
	v_lshlrev_b32_e32 v202, 16, v229
	v_and_b32_e32 v203, 0xffff0000, v229
	v_pk_add_f32 v[16:17], v[16:17], v[202:203]
	v_fmac_f32_e32 v239, v16, v16
	v_fmac_f32_e32 v243, v17, v17
	v_lshlrev_b32_e32 v202, 16, v230
	v_and_b32_e32 v203, 0xffff0000, v230
	v_pk_add_f32 v[10:11], v[10:11], v[202:203]
	v_fmac_f32_e32 v239, v10, v10
	v_fmac_f32_e32 v243, v11, v11
	v_lshlrev_b32_e32 v202, 16, v231
	v_and_b32_e32 v203, 0xffff0000, v231
	v_pk_add_f32 v[12:13], v[12:13], v[202:203]
	v_fmac_f32_e32 v239, v12, v12
	v_fmac_f32_e32 v243, v13, v13
	v_cvt_pk_bf16_f32 v228, v14, v15
	v_cvt_pk_bf16_f32 v229, v16, v17
	v_cvt_pk_bf16_f32 v230, v10, v11
	v_cvt_pk_bf16_f32 v231, v12, v13
	global_store_dwordx4 v[200:201], v[228:231], off
	v_lshlrev_b32_e32 v202, 16, v232
	v_and_b32_e32 v203, 0xffff0000, v232
	v_pk_add_f32 v[6:7], v[6:7], v[202:203]
	v_fmac_f32_e32 v239, v6, v6
	v_fmac_f32_e32 v243, v7, v7
	v_lshlrev_b32_e32 v202, 16, v233
	v_and_b32_e32 v203, 0xffff0000, v233
	v_pk_add_f32 v[8:9], v[8:9], v[202:203]
	v_fmac_f32_e32 v239, v8, v8
	v_fmac_f32_e32 v243, v9, v9
	v_lshlrev_b32_e32 v202, 16, v234
	v_and_b32_e32 v203, 0xffff0000, v234
	v_pk_add_f32 v[2:3], v[2:3], v[202:203]
	v_fmac_f32_e32 v239, v2, v2
	v_fmac_f32_e32 v243, v3, v3
	v_lshlrev_b32_e32 v202, 16, v235
	v_and_b32_e32 v203, 0xffff0000, v235
	v_pk_add_f32 v[4:5], v[4:5], v[202:203]
	v_fmac_f32_e32 v239, v4, v4
	v_fmac_f32_e32 v243, v5, v5
	v_cvt_pk_bf16_f32 v232, v6, v7
	v_cvt_pk_bf16_f32 v233, v8, v9
	v_cvt_pk_bf16_f32 v234, v2, v3
	v_cvt_pk_bf16_f32 v235, v4, v5
	global_store_dwordx4 v[200:201], v[232:235], off offset:256
	v_add_f32_e32 v239, v239, v243
	ds_bpermute_b32 v240, v244, v236
	ds_bpermute_b32 v241, v244, v237
	ds_bpermute_b32 v242, v244, v238
	ds_bpermute_b32 v243, v244, v239
	s_ashr_i32 s25, s24, 31
	s_lshl_b64 s[60:61], s[24:25], 19
	s_add_u32 s60, s70, s60
	s_addc_u32 s61, s71, s61
	s_waitcnt lgkmcnt(0)
	v_add_f32_e32 v236, v236, v240
	v_add_f32_e32 v237, v237, v241
	v_add_f32_e32 v238, v238, v242
	v_add_f32_e32 v239, v239, v243
	ds_bpermute_b32 v240, v245, v236
	ds_bpermute_b32 v241, v245, v237
	ds_bpermute_b32 v242, v245, v238
	ds_bpermute_b32 v243, v245, v239
	v_lshl_add_u64 v[204:205], v[186:187], 4, s[60:61]
	v_lshl_add_u64 v[204:205], s[54:55], 2, v[204:205]
	v_lshl_add_u64 v[212:213], v[188:189], 4, s[60:61]
	v_lshl_add_u64 v[212:213], s[54:55], 2, v[212:213]
	v_lshl_add_u64 v[220:221], v[190:191], 4, s[60:61]
	v_lshl_add_u64 v[220:221], s[54:55], 2, v[220:221]
	v_lshl_add_u64 v[228:229], v[192:193], 4, s[60:61]
	v_lshl_add_u64 v[228:229], s[54:55], 2, v[228:229]
	s_waitcnt lgkmcnt(0)
	v_add_f32_e32 v236, v236, v240
	v_add_f32_e32 v237, v237, v241
	v_add_f32_e32 v238, v238, v242
	v_add_f32_e32 v239, v239, v243
	s_and_saveexec_b64 s[10:11], s[42:43]
	global_store_dword v[204:205], v236, off
	global_store_dword v[212:213], v237, off
	global_store_dword v[220:221], v238, off
	global_store_dword v[228:229], v239, off
	s_or_b64 exec, exec, s[10:11]

; __device__ __forceinline__ int fresh_tid() { int t = threadIdx.x; asm volatile("" : "+v"(t)); return t; }
; #define PG8_STAGE(bufoff, gbase, voff) do { _Pragma("unroll") for (int _i = 0; _i < 2; ++_i) \
;         __builtin_amdgcn_global_load_lds((const unsigned*)((const char*)(gbase) + (voff)[_i]), (LAS unsigned*)(lds + (bufoff) + ldsw + _i * 8192), 16, 0, 0); } while (0)
; #define PG8_WAIT_V(n) asm volatile("s_waitcnt vmcnt(" #n ")" ::: "memory")
; template <class Epi, class Sched, int NSEG, int KK, int LDA, int LDB>
; __device__ __forceinline__ void gemm_phase(LAS unsigned char* lds, const Gemm g, const Sched& S, const Epi& E) {
;     const int tid = fresh_tid(), wid = __builtin_amdgcn_readfirstlane(tid >> 6), lane = tid & 63, wr = wid >> 2, wc = wid & 3, fr = lane & 15, fq = lane >> 4;
;     constexpr int nt = KK / BK;
;     unsigned voffA[2], voffB[2];
; #pragma unroll
;     for (int i = 0; i < 2; ++i) { int R, C; stage_rc(tid * 16 + i * 8192, R, C); const int Rb = Epi::PERM ? ((R & ~31) + perm32(R & 31)) : R;
;         voffA[i] = (unsigned)(R * LDA + C) * 2u; voffB[i] = (unsigned)(Rb * LDB + C) * 2u; }
;     constexpr size_t kstep = (size_t)(BK * 2);
;     constexpr size_t hstepA = (size_t)HALF * LDA * 2, hstepB = (size_t)HALF * LDB * 2;
;     constexpr size_t tstepA = 2 * hstepA, tstepB = 2 * hstepB;
;     const unsigned ldsw = (unsigned)wid * 1024u;
;     const int aoff = lds_byte(wr * 64 + fr, fq * 8), boff = lds_byte(wc * 32 + fr, fq * 8);
;     ...
;     Unit cur, nxt; int ui = 0;
;     if (!S.next(0, cur)) return;
;     f32x4 acc[2][2][4][2];
; #pragma unroll
;     for (int a = 0; a < 2; ++a)
; #pragma unroll
;         for (int b = 0; b < 2; ++b)
; #pragma unroll
;             for (int m = 0; m < 4; ++m)
; #pragma unroll
;                 for (int n = 0; n < 2; ++n) acc[a][b][m][n] = (f32x4){0.f, 0.f, 0.f, 0.f};
;     bf16x8 At[4][2], B0[2][2], B1[2][2];
;     const char* cA = PG8_APTR(cur); const char* cB = PG8_BPTR(cur);
;     PG8_STAGE(PG8_SB(0, 0), cB, voffB); PG8_STAGE(PG8_SB(0, 1), cB + hstepB, voffB); PG8_STAGE(PG8_SA(0, 0), cA, voffA); PG8_STAGE(PG8_SA(0, 1), cA + hstepA, voffA);
;     if (wr == 1) PG8_BAR;
;     PG8_WAIT_V(2); PG8_BAR;
;     PG8_STAGE(PG8_SB(1, 0), cB + kstep, voffB); PG8_STAGE(PG8_SA(1, 0), cA + kstep, voffA); PG8_STAGE(PG8_SB(1, 1), cB + hstepB + kstep, voffB);
;     PG8_WAIT_V(6); PG8_BAR;
.LBB0_1244:
	v_and_b32_e32 v11, 15, v10
	v_and_b32_e32 v20, 48, v10
	v_lshlrev_b32_e32 v10, 2, v10
	s_and_b32 s52, s9, 3
	v_lshl_or_b32 v11, v11, 6, v20
	s_lshl_b32 s9, s12, 13
	v_and_b32_e32 v10, 32, v10
	v_lshl_add_u64 v[12:13], s[46:47], 0, v[0:1]
	v_mov_b32_e32 v131, v1
	v_readlane_b32 s42, v254, 5
	v_bitop3_b32 v20, v11, s9, v10 bitop3:0xde
	s_lshl_b32 s9, s52, 12
	v_lshl_add_u64 v[14:15], s[46:47], 0, v[130:131]
	v_readlane_b32 s43, v254, 6
	v_bitop3_b32 v164, v11, s9, v10 bitop3:0xde
	v_and_b32_e32 v218, 3, v246
	v_bfe_u32 v219, v246, 2, 1
	v_bfe_u32 v220, v246, 3, 1
	v_bfe_u32 v221, v246, 4, 2
	v_lshlrev_b32_e32 v218, 6, v218
	v_lshl_or_b32 v218, v219, 9, v218
	v_lshl_or_b32 v218, v221, 4, v218
	v_lshlrev_b32_e32 v219, 5, v219
	v_xor_b32_e32 v218, v218, v219
	v_lshl_or_b32 v218, v220, 11, v218
	v_or_b32_e32 v164, s9, v218
	s_add_i32 m0, s48, 0x18000
	v_lshl_add_u64 v[10:11], v[12:13], 0, s[28:29]
	v_lshl_add_u64 v[16:17], s[42:43], 0, v[0:1]
	s_waitcnt vmcnt(2)
	s_barrier
	global_load_lds_dwordx4 v[10:11], off
	v_lshl_add_u64 v[10:11], v[14:15], 0, s[28:29]
	s_add_i32 m0, s48, 0x1a000
	s_add_i32 s53, s48, 0x8000
	s_add_i32 s54, s48, 0xa000
	v_lshl_add_u64 v[18:19], s[42:43], 0, v[130:131]
	global_load_lds_dwordx4 v[10:11], off
	v_lshl_add_u64 v[10:11], v[16:17], 0, s[28:29]
	s_mov_b32 m0, s53
	s_add_u32 s10, s46, 0xb0080
	global_load_lds_dwordx4 v[10:11], off
	v_lshl_add_u64 v[10:11], v[18:19], 0, s[28:29]
	s_mov_b32 m0, s54
	s_addc_u32 s11, s47, 0
	global_load_lds_dwordx4 v[10:11], off
	s_add_i32 m0, s48, 0x1c000
	v_lshl_add_u64 v[10:11], s[10:11], 0, v[0:1]
	global_load_lds_dwordx4 v[10:11], off
	v_lshl_add_u64 v[10:11], s[10:11], 0, v[130:131]
	s_add_i32 m0, s48, 0x1e000
	s_movk_i32 s22, 0xb00
	global_load_lds_dwordx4 v[10:11], off
	v_lshrrev_b32_e32 v7, 1, v7
	v_mul_lo_u32 v6, v6, s22
	v_mad_u64_u32 v[6:7], s[10:11], v7, s80, v[6:7]
	v_or_b32_e32 v6, v6, v8
	v_add_lshl_u32 v6, v6, v9, 1
	v_mov_b32_e32 v7, v1
	s_mov_b64 s[24:25], 0xb0080
	v_lshl_add_u64 v[132:133], v[6:7], 0, s[24:25]
	v_lshrrev_b32_e32 v6, 1, v2
	v_mul_lo_u32 v2, v3, s22
	v_mad_u64_u32 v[2:3], s[10:11], v6, s80, v[2:3]
	s_waitcnt vmcnt(6)
	v_or_b32_e32 v2, v2, v4
	v_readlane_b32 s10, v255, 46
	s_cmpk_lt_u32 s8, 0x100
	v_add_lshl_u32 v2, v2, v5, 1
	v_mov_b32_e32 v3, v1
	s_mov_b32 s22, s10
	v_readlane_b32 s10, v254, 3
	s_cselect_b64 s[8:9], -1, 0
	v_lshl_add_u64 v[134:135], v[2:3], 0, s[24:25]
	s_mov_b32 s55, 0
	v_add_u32_e32 v165, 0, v20
	s_mov_b32 s23, s10
	s_barrier
	v_readlane_b32 s11, v254, 4
	s_branch .LBB0_1247

; #define PG8_STAGE(bufoff, gbase, voff) do { _Pragma("unroll") for (int _i = 0; _i < 2; ++_i) \
;         __builtin_amdgcn_global_load_lds((const unsigned*)((const char*)(gbase) + (voff)[_i]), (LAS unsigned*)(lds + (bufoff) + ldsw + _i * 8192), 16, 0, 0); } while (0)
; #define PG8_LDA(dst, b, h) do { _Pragma("unroll") for (int m = 0; m < 4; ++m) _Pragma("unroll") for (int k = 0; k < 2; ++k) dst[m][k] = *(const LAS bf16x8*)(lds + PG8_SA(b, h) + aoff + m * 2048 + k * 1024); } while (0)
; #define PG8_LDB(dst, b, h) do { _Pragma("unroll") for (int n = 0; n < 2; ++n) _Pragma("unroll") for (int k = 0; k < 2; ++k) dst[n][k] = *(const LAS bf16x8*)(lds + PG8_SB(b, h) + boff + n * 2048 + k * 1024); } while (0)
; #define PG8_MMA(ai, bj, At, Bt) do { __builtin_amdgcn_s_setprio(1); _Pragma("unroll") for (int m = 0; m < 4; ++m) _Pragma("unroll") for (int n = 0; n < 2; ++n) _Pragma("unroll") for (int k = 0; k < 2; ++k) \
;         acc[ai][bj][m][n] = __builtin_amdgcn_mfma_f32_16x16x32_bf16(Bt[n][k], At[m][k], acc[ai][bj][m][n], 0, 0, 0); __builtin_amdgcn_s_setprio(0); } while (0)
; #define PG8_WAIT_V(n) asm volatile("s_waitcnt vmcnt(" #n ")" ::: "memory")
; #define PG8_WAIT_L(n) asm volatile("s_waitcnt lgkmcnt(" #n ")" ::: "memory")
; #define PG8_BAR __builtin_amdgcn_s_barrier()
; #define PG8_SCHED __builtin_amdgcn_sched_barrier(0)
; template <class Epi, class Sched, int NSEG, int KK, int LDA, int LDB>
; __device__ __forceinline__ void gemm_phase(LAS unsigned char* lds, const Gemm g, const Sched& S, const Epi& E) {
;     ...
;             const char* a1 = cA + (size_t)(t + 1) * kstep;
;             const char* a2 = last ? nA : cA + (size_t)(t + 2) * kstep; const char* b2 = last ? nB : cB + (size_t)(t + 2) * kstep;
;             const char* a3 = a2 + kstep; const char* b3 = b2 + kstep;
;             PG8_LDB(B0, 0, 0); PG8_LDB(B1, 0, 1); PG8_SCHED; PG8_LDA(At, 0, 0); PG8_STAGE(PG8_SA(1, 1), a1 + hstepA, voffA);
;             PG8_WAIT_V(8); PG8_WAIT_L(0); PG8_BAR; PG8_MMA(0, 0, At, B0); PG8_MMA(0, 1, At, B1); PG8_BAR; PG8_SCHED;
;             PG8_LDA(At, 0, 1); PG8_STAGE(PG8_SB(0, 0), b2, voffB); PG8_STAGE(PG8_SB(0, 1), b2 + hstepB, voffB); PG8_STAGE(PG8_SA(0, 0), a2, voffA);
.LBB0_1258:
	s_add_u32 s40, s42, 0x100
	s_addc_u32 s41, s43, 0
	s_add_i32 s61, 0, 0x10000
	s_cmp_eq_u32 s60, 40
	s_cselect_b32 s47, s25, s41
	s_cselect_b32 s46, s24, s40
	s_cselect_b32 s11, s45, s59
	s_cselect_b32 s10, s44, s58
	s_add_i32 s62, 0, 0x14000
	v_add_u32_e32 v148, s61, v164
	v_add_u32_e32 v166, s62, v164
	ds_read_b128 v[136:139], v148
	ds_read_b128 v[140:143], v148 offset:1024
	ds_read_b128 v[144:147], v148 offset:256
	ds_read_b128 v[148:151], v148 offset:1280
	ds_read_b128 v[152:155], v166
	ds_read_b128 v[156:159], v166 offset:1024
	ds_read_b128 v[160:163], v166 offset:256
	ds_read_b128 v[176:179], v166 offset:1280
	v_lshl_add_u64 v[166:167], s[42:43], 0, v[132:133]
	s_add_i32 m0, s48, 0xc000
	ds_read_b128 v[180:183], v165
	ds_read_b128 v[184:187], v165 offset:1024
	ds_read_b128 v[188:191], v165 offset:2048
	ds_read_b128 v[192:195], v165 offset:3072
	ds_read_b128 v[196:199], v165 offset:4096
	ds_read_b128 v[200:203], v165 offset:5120
	ds_read_b128 v[204:207], v165 offset:6144
	ds_read_b128 v[208:211], v165 offset:7168
	global_load_lds_dwordx4 v[166:167], off
	v_lshl_add_u64 v[166:167], s[42:43], 0, v[134:135]
	s_add_i32 m0, s48, 0xe000
	s_nop 0
	global_load_lds_dwordx4 v[166:167], off
	s_waitcnt vmcnt(8)
	s_waitcnt lgkmcnt(0)
	s_barrier
	s_setprio 1
	s_waitcnt lgkmcnt(0)
	v_mfma_f32_16x16x32_bf16 v[126:129], v[136:139], v[180:183], v[126:129]
	v_mfma_f32_16x16x32_bf16 v[122:125], v[144:147], v[180:183], v[122:125]
	v_mfma_f32_16x16x32_bf16 v[110:113], v[136:139], v[188:191], v[110:113]
	v_mfma_f32_16x16x32_bf16 v[106:109], v[144:147], v[188:191], v[106:109]
	v_mfma_f32_16x16x32_bf16 v[94:97], v[136:139], v[196:199], v[94:97]
	v_mfma_f32_16x16x32_bf16 v[90:93], v[144:147], v[196:199], v[90:93]
	v_mfma_f32_16x16x32_bf16 v[78:81], v[136:139], v[204:207], v[78:81]
	v_mfma_f32_16x16x32_bf16 v[74:77], v[144:147], v[204:207], v[74:77]
	v_mfma_f32_16x16x32_bf16 v[126:129], v[140:143], v[184:187], v[126:129]
	v_mfma_f32_16x16x32_bf16 v[122:125], v[148:151], v[184:187], v[122:125]
	v_mfma_f32_16x16x32_bf16 v[110:113], v[140:143], v[192:195], v[110:113]
	v_mfma_f32_16x16x32_bf16 v[106:109], v[148:151], v[192:195], v[106:109]
	v_mfma_f32_16x16x32_bf16 v[94:97], v[140:143], v[200:203], v[94:97]
	v_mfma_f32_16x16x32_bf16 v[90:93], v[148:151], v[200:203], v[90:93]
	v_mfma_f32_16x16x32_bf16 v[78:81], v[140:143], v[208:211], v[78:81]
	v_mfma_f32_16x16x32_bf16 v[74:77], v[148:151], v[208:211], v[74:77]
	s_setprio 0
	s_setprio 1
	v_mfma_f32_16x16x32_bf16 v[118:121], v[152:155], v[180:183], v[118:121]
	v_mfma_f32_16x16x32_bf16 v[114:117], v[160:163], v[180:183], v[114:117]
	v_mfma_f32_16x16x32_bf16 v[102:105], v[152:155], v[188:191], v[102:105]
	v_mfma_f32_16x16x32_bf16 v[98:101], v[160:163], v[188:191], v[98:101]
	v_mfma_f32_16x16x32_bf16 v[86:89], v[152:155], v[196:199], v[86:89]
	v_mfma_f32_16x16x32_bf16 v[82:85], v[160:163], v[196:199], v[82:85]
	v_mfma_f32_16x16x32_bf16 v[70:73], v[152:155], v[204:207], v[70:73]
	v_mfma_f32_16x16x32_bf16 v[66:69], v[160:163], v[204:207], v[66:69]
	v_mfma_f32_16x16x32_bf16 v[118:121], v[156:159], v[184:187], v[118:121]
	v_mfma_f32_16x16x32_bf16 v[114:117], v[176:179], v[184:187], v[114:117]
	v_mfma_f32_16x16x32_bf16 v[102:105], v[156:159], v[192:195], v[102:105]
	v_mfma_f32_16x16x32_bf16 v[98:101], v[176:179], v[192:195], v[98:101]
	v_mfma_f32_16x16x32_bf16 v[86:89], v[156:159], v[200:203], v[86:89]
	v_mfma_f32_16x16x32_bf16 v[82:85], v[176:179], v[200:203], v[82:85]
	v_mfma_f32_16x16x32_bf16 v[70:73], v[156:159], v[208:211], v[70:73]
	v_mfma_f32_16x16x32_bf16 v[66:69], v[176:179], v[208:211], v[66:69]
	s_setprio 0
	s_barrier
	s_add_i32 s42, s61, s13
	v_lshl_add_u64 v[166:167], s[10:11], 0, v[0:1]
	s_mov_b32 m0, s42
	ds_read_b128 v[180:183], v165 offset:16384
	ds_read_b128 v[184:187], v165 offset:17408
	ds_read_b128 v[188:191], v165 offset:18432
	ds_read_b128 v[192:195], v165 offset:19456
	ds_read_b128 v[196:199], v165 offset:20480
	ds_read_b128 v[200:203], v165 offset:21504
	ds_read_b128 v[204:207], v165 offset:22528
	ds_read_b128 v[208:211], v165 offset:23552
	global_load_lds_dwordx4 v[166:167], off
	s_add_i32 m0, s42, 0x2000
	s_add_u32 s42, s10, 0xb0000
	v_lshl_add_u64 v[172:173], s[10:11], 0, v[130:131]
	s_addc_u32 s43, s11, 0
	s_add_i32 s61, s62, s13
	global_load_lds_dwordx4 v[172:173], off
	v_lshl_add_u64 v[212:213], s[42:43], 0, v[0:1]
	s_mov_b32 m0, s61
	v_lshl_add_u64 v[214:215], s[46:47], 0, v[130:131]
	global_load_lds_dwordx4 v[212:213], off
	v_lshl_add_u64 v[212:213], s[42:43], 0, v[130:131]
	s_add_i32 m0, s61, 0x2000
	s_nop 0
	global_load_lds_dwordx4 v[212:213], off
	v_lshl_add_u64 v[212:213], s[46:47], 0, v[0:1]
	s_mov_b32 m0, s48
	s_nop 0
	global_load_lds_dwordx4 v[212:213], off
	s_mov_b32 m0, s49
	s_nop 0
	global_load_lds_dwordx4 v[214:215], off
	s_waitcnt vmcnt(8)
	s_waitcnt lgkmcnt(0)
	s_barrier
; #define PG8_STAGE(bufoff, gbase, voff) do { _Pragma("unroll") for (int _i = 0; _i < 2; ++_i) \
;         __builtin_amdgcn_global_load_lds((const unsigned*)((const char*)(gbase) + (voff)[_i]), (LAS unsigned*)(lds + (bufoff) + ldsw + _i * 8192), 16, 0, 0); } while (0)
; #define PG8_LDA(dst, b, h) do { _Pragma("unroll") for (int m = 0; m < 4; ++m) _Pragma("unroll") for (int k = 0; k < 2; ++k) dst[m][k] = *(const LAS bf16x8*)(lds + PG8_SA(b, h) + aoff + m * 2048 + k * 1024); } while (0)
; #define PG8_LDB(dst, b, h) do { _Pragma("unroll") for (int n = 0; n < 2; ++n) _Pragma("unroll") for (int k = 0; k < 2; ++k) dst[n][k] = *(const LAS bf16x8*)(lds + PG8_SB(b, h) + boff + n * 2048 + k * 1024); } while (0)
; #define PG8_MMA(ai, bj, At, Bt) do { __builtin_amdgcn_s_setprio(1); _Pragma("unroll") for (int m = 0; m < 4; ++m) _Pragma("unroll") for (int n = 0; n < 2; ++n) _Pragma("unroll") for (int k = 0; k < 2; ++k) \
;         acc[ai][bj][m][n] = __builtin_amdgcn_mfma_f32_16x16x32_bf16(Bt[n][k], At[m][k], acc[ai][bj][m][n], 0, 0, 0); __builtin_amdgcn_s_setprio(0); } while (0)
; #define PG8_WAIT_V(n) asm volatile("s_waitcnt vmcnt(" #n ")" ::: "memory")
; #define PG8_WAIT_L(n) asm volatile("s_waitcnt lgkmcnt(" #n ")" ::: "memory")
; #define PG8_BAR __builtin_amdgcn_s_barrier()
; #define PG8_SCHED __builtin_amdgcn_sched_barrier(0)
; template <class Epi, class Sched, int NSEG, int KK, int LDA, int LDB>
; __device__ __forceinline__ void gemm_phase(LAS unsigned char* lds, const Gemm g, const Sched& S, const Epi& E) {
;     ...
;             PG8_WAIT_V(8); PG8_WAIT_L(0); PG8_BAR; PG8_MMA(1, 0, At, B0); PG8_MMA(1, 1, At, B1); PG8_BAR; PG8_SCHED;
;             PG8_LDB(B0, 1, 0); PG8_LDB(B1, 1, 1); PG8_SCHED; PG8_LDA(At, 1, 0); PG8_STAGE(PG8_SA(0, 1), a2 + hstepA, voffA);
;             PG8_WAIT_V(8); PG8_WAIT_L(0); PG8_BAR; PG8_MMA(0, 0, At, B0); PG8_MMA(0, 1, At, B1); PG8_BAR; PG8_SCHED;
	s_setprio 1
	s_waitcnt lgkmcnt(0)
	v_mfma_f32_16x16x32_bf16 v[62:65], v[136:139], v[180:183], v[62:65]
	v_mfma_f32_16x16x32_bf16 v[58:61], v[144:147], v[180:183], v[58:61]
	v_mfma_f32_16x16x32_bf16 v[46:49], v[136:139], v[188:191], v[46:49]
	v_mfma_f32_16x16x32_bf16 v[42:45], v[144:147], v[188:191], v[42:45]
	v_mfma_f32_16x16x32_bf16 v[30:33], v[136:139], v[196:199], v[30:33]
	v_mfma_f32_16x16x32_bf16 v[26:29], v[144:147], v[196:199], v[26:29]
	v_mfma_f32_16x16x32_bf16 v[14:17], v[136:139], v[204:207], v[14:17]
	v_mfma_f32_16x16x32_bf16 v[10:13], v[144:147], v[204:207], v[10:13]
	v_mfma_f32_16x16x32_bf16 v[62:65], v[140:143], v[184:187], v[62:65]
	v_mfma_f32_16x16x32_bf16 v[58:61], v[148:151], v[184:187], v[58:61]
	v_mfma_f32_16x16x32_bf16 v[46:49], v[140:143], v[192:195], v[46:49]
	v_mfma_f32_16x16x32_bf16 v[42:45], v[148:151], v[192:195], v[42:45]
	v_mfma_f32_16x16x32_bf16 v[30:33], v[140:143], v[200:203], v[30:33]
	v_mfma_f32_16x16x32_bf16 v[26:29], v[148:151], v[200:203], v[26:29]
	v_mfma_f32_16x16x32_bf16 v[14:17], v[140:143], v[208:211], v[14:17]
	v_mfma_f32_16x16x32_bf16 v[10:13], v[148:151], v[208:211], v[10:13]
	s_setprio 0
	s_setprio 1
	v_mfma_f32_16x16x32_bf16 v[54:57], v[152:155], v[180:183], v[54:57]
	v_mfma_f32_16x16x32_bf16 v[50:53], v[160:163], v[180:183], v[50:53]
	v_mfma_f32_16x16x32_bf16 v[38:41], v[152:155], v[188:191], v[38:41]
	v_mfma_f32_16x16x32_bf16 v[34:37], v[160:163], v[188:191], v[34:37]
	v_mfma_f32_16x16x32_bf16 v[22:25], v[152:155], v[196:199], v[22:25]
	v_mfma_f32_16x16x32_bf16 v[18:21], v[160:163], v[196:199], v[18:21]
	v_mfma_f32_16x16x32_bf16 v[6:9], v[152:155], v[204:207], v[6:9]
	v_mfma_f32_16x16x32_bf16 v[2:5], v[160:163], v[204:207], v[2:5]
	v_mfma_f32_16x16x32_bf16 v[54:57], v[156:159], v[184:187], v[54:57]
	v_mfma_f32_16x16x32_bf16 v[50:53], v[176:179], v[184:187], v[50:53]
	v_mfma_f32_16x16x32_bf16 v[38:41], v[156:159], v[192:195], v[38:41]
	v_mfma_f32_16x16x32_bf16 v[34:37], v[176:179], v[192:195], v[34:37]
	v_mfma_f32_16x16x32_bf16 v[22:25], v[156:159], v[200:203], v[22:25]
	v_mfma_f32_16x16x32_bf16 v[18:21], v[176:179], v[200:203], v[18:21]
	v_mfma_f32_16x16x32_bf16 v[6:9], v[156:159], v[208:211], v[6:9]
	v_mfma_f32_16x16x32_bf16 v[2:5], v[176:179], v[208:211], v[2:5]
	s_setprio 0
	s_barrier
	s_add_i32 s61, 0, 0x18000
	s_add_i32 s62, 0, 0x1c000
	v_add_u32_e32 v148, s61, v164
	v_add_u32_e32 v176, s62, v164
	ds_read_b128 v[136:139], v148
	ds_read_b128 v[140:143], v148 offset:1024
	ds_read_b128 v[144:147], v148 offset:256
	ds_read_b128 v[148:151], v148 offset:1280
	ds_read_b128 v[152:155], v176
	ds_read_b128 v[156:159], v176 offset:1024
	ds_read_b128 v[160:163], v176 offset:256
	ds_read_b128 v[176:179], v176 offset:1280
	s_add_u32 s42, s46, 0xb0000
	s_addc_u32 s43, s47, 0
	s_mov_b32 m0, s50
	v_lshl_add_u64 v[216:217], s[42:43], 0, v[0:1]
	ds_read_b128 v[180:183], v165 offset:32768
	ds_read_b128 v[184:187], v165 offset:33792
	ds_read_b128 v[188:191], v165 offset:34816
	ds_read_b128 v[192:195], v165 offset:35840
	ds_read_b128 v[196:199], v165 offset:36864
	ds_read_b128 v[200:203], v165 offset:37888
	ds_read_b128 v[204:207], v165 offset:38912
	ds_read_b128 v[208:211], v165 offset:39936
	global_load_lds_dwordx4 v[216:217], off
	v_lshl_add_u64 v[216:217], s[42:43], 0, v[130:131]
	s_mov_b32 m0, s51
	s_nop 0
	global_load_lds_dwordx4 v[216:217], off
	s_waitcnt vmcnt(8)
	s_waitcnt lgkmcnt(0)
	s_barrier
	s_setprio 1
	s_waitcnt lgkmcnt(0)
	v_mfma_f32_16x16x32_bf16 v[126:129], v[136:139], v[180:183], v[126:129]
	v_mfma_f32_16x16x32_bf16 v[122:125], v[144:147], v[180:183], v[122:125]
	v_mfma_f32_16x16x32_bf16 v[110:113], v[136:139], v[188:191], v[110:113]
	v_mfma_f32_16x16x32_bf16 v[106:109], v[144:147], v[188:191], v[106:109]
	v_mfma_f32_16x16x32_bf16 v[94:97], v[136:139], v[196:199], v[94:97]
	v_mfma_f32_16x16x32_bf16 v[90:93], v[144:147], v[196:199], v[90:93]
	v_mfma_f32_16x16x32_bf16 v[78:81], v[136:139], v[204:207], v[78:81]
	v_mfma_f32_16x16x32_bf16 v[74:77], v[144:147], v[204:207], v[74:77]
	v_mfma_f32_16x16x32_bf16 v[126:129], v[140:143], v[184:187], v[126:129]
	v_mfma_f32_16x16x32_bf16 v[122:125], v[148:151], v[184:187], v[122:125]
	v_mfma_f32_16x16x32_bf16 v[110:113], v[140:143], v[192:195], v[110:113]
	v_mfma_f32_16x16x32_bf16 v[106:109], v[148:151], v[192:195], v[106:109]
	v_mfma_f32_16x16x32_bf16 v[94:97], v[140:143], v[200:203], v[94:97]
	v_mfma_f32_16x16x32_bf16 v[90:93], v[148:151], v[200:203], v[90:93]
	v_mfma_f32_16x16x32_bf16 v[78:81], v[140:143], v[208:211], v[78:81]
	v_mfma_f32_16x16x32_bf16 v[74:77], v[148:151], v[208:211], v[74:77]
	s_setprio 0
	s_setprio 1
	v_mfma_f32_16x16x32_bf16 v[118:121], v[152:155], v[180:183], v[118:121]
	v_mfma_f32_16x16x32_bf16 v[114:117], v[160:163], v[180:183], v[114:117]
	v_mfma_f32_16x16x32_bf16 v[102:105], v[152:155], v[188:191], v[102:105]
	v_mfma_f32_16x16x32_bf16 v[98:101], v[160:163], v[188:191], v[98:101]
	v_mfma_f32_16x16x32_bf16 v[86:89], v[152:155], v[196:199], v[86:89]
	v_mfma_f32_16x16x32_bf16 v[82:85], v[160:163], v[196:199], v[82:85]
	v_mfma_f32_16x16x32_bf16 v[70:73], v[152:155], v[204:207], v[70:73]
	v_mfma_f32_16x16x32_bf16 v[66:69], v[160:163], v[204:207], v[66:69]
	v_mfma_f32_16x16x32_bf16 v[118:121], v[156:159], v[184:187], v[118:121]
	v_mfma_f32_16x16x32_bf16 v[114:117], v[176:179], v[184:187], v[114:117]
	v_mfma_f32_16x16x32_bf16 v[102:105], v[156:159], v[192:195], v[102:105]
	v_mfma_f32_16x16x32_bf16 v[98:101], v[176:179], v[192:195], v[98:101]
	v_mfma_f32_16x16x32_bf16 v[86:89], v[156:159], v[200:203], v[86:89]
	v_mfma_f32_16x16x32_bf16 v[82:85], v[176:179], v[200:203], v[82:85]
	v_mfma_f32_16x16x32_bf16 v[70:73], v[156:159], v[208:211], v[70:73]
	v_mfma_f32_16x16x32_bf16 v[66:69], v[176:179], v[208:211], v[66:69]
	s_setprio 0
	s_barrier
; __device__ __forceinline__ int fresh_tid() { int t = threadIdx.x; asm volatile("" : "+v"(t)); return t; }
; #define PG8_STAGE(bufoff, gbase, voff) do { _Pragma("unroll") for (int _i = 0; _i < 2; ++_i) \
;         __builtin_amdgcn_global_load_lds((const unsigned*)((const char*)(gbase) + (voff)[_i]), (LAS unsigned*)(lds + (bufoff) + ldsw + _i * 8192), 16, 0, 0); } while (0)
; #define PG8_LDA(dst, b, h) do { _Pragma("unroll") for (int m = 0; m < 4; ++m) _Pragma("unroll") for (int k = 0; k < 2; ++k) dst[m][k] = *(const LAS bf16x8*)(lds + PG8_SA(b, h) + aoff + m * 2048 + k * 1024); } while (0)
; #define PG8_MMA(ai, bj, At, Bt) do { __builtin_amdgcn_s_setprio(1); _Pragma("unroll") for (int m = 0; m < 4; ++m) _Pragma("unroll") for (int n = 0; n < 2; ++n) _Pragma("unroll") for (int k = 0; k < 2; ++k) \
;         acc[ai][bj][m][n] = __builtin_amdgcn_mfma_f32_16x16x32_bf16(Bt[n][k], At[m][k], acc[ai][bj][m][n], 0, 0, 0); __builtin_amdgcn_s_setprio(0); } while (0)
; #define PG8_WAIT_V(n) asm volatile("s_waitcnt vmcnt(" #n ")" ::: "memory")
; #define PG8_WAIT_L(n) asm volatile("s_waitcnt lgkmcnt(" #n ")" ::: "memory")
; #define PG8_BAR __builtin_amdgcn_s_barrier()
; #define PG8_SCHED __builtin_amdgcn_sched_barrier(0)
;     __device__ __forceinline__ void operator()(f32x4 (&acc)[2][2][4][2], const Unit& u, int wr, int wc, int fr, int fq) const {
;         const int col0 = u.pn * BM + wc * 32 + 4 * fq;
; #pragma unroll
; template <class Epi, class Sched, int NSEG, int KK, int LDA, int LDB>
; __device__ __forceinline__ void gemm_phase(LAS unsigned char* lds, const Gemm g, const Sched& S, const Epi& E) {
;     ...
;             PG8_LDA(At, 1, 1); PG8_STAGE(PG8_SB(1, 0), b3, voffB); PG8_STAGE(PG8_SB(1, 1), b3 + hstepB, voffB); PG8_STAGE(PG8_SA(1, 0), a3, voffA);
;             PG8_WAIT_V(8); PG8_WAIT_L(0); PG8_BAR; PG8_MMA(1, 0, At, B0); PG8_MMA(1, 1, At, B1); PG8_BAR; PG8_SCHED;
;         }
;         if (wr == 0) PG8_BAR;
;         { const int t_e = fresh_tid(); int fr_e = t_e & 15, fq_e = (t_e >> 4) & 3; int wr_e = wr, wc_e = wc; asm volatile("" : "+s"(wr_e), "+s"(wc_e));
	s_add_i32 s42, s61, s13
	v_lshl_add_u64 v[166:167], v[166:167], 0, s[28:29]
	s_mov_b32 m0, s42
	ds_read_b128 v[180:183], v165 offset:49152
	ds_read_b128 v[184:187], v165 offset:50176
	ds_read_b128 v[188:191], v165 offset:51200
	ds_read_b128 v[192:195], v165 offset:52224
	ds_read_b128 v[196:199], v165 offset:53248
	ds_read_b128 v[200:203], v165 offset:54272
	ds_read_b128 v[204:207], v165 offset:55296
	ds_read_b128 v[208:211], v165 offset:56320
	global_load_lds_dwordx4 v[166:167], off
	s_add_i32 m0, s42, 0x2000
	s_add_u32 s10, s10, 0xb0080
	v_lshl_add_u64 v[166:167], v[172:173], 0, s[28:29]
	s_addc_u32 s11, s11, 0
	s_add_i32 s42, s62, s13
	global_load_lds_dwordx4 v[166:167], off
	v_lshl_add_u64 v[166:167], s[10:11], 0, v[0:1]
	s_mov_b32 m0, s42
	s_nop 0
	global_load_lds_dwordx4 v[166:167], off
	v_lshl_add_u64 v[166:167], s[10:11], 0, v[130:131]
	s_add_i32 m0, s42, 0x2000
	s_nop 0
	global_load_lds_dwordx4 v[166:167], off
	v_lshl_add_u64 v[166:167], v[212:213], 0, s[28:29]
	s_mov_b32 m0, s53
	s_nop 0
	global_load_lds_dwordx4 v[166:167], off
	v_lshl_add_u64 v[166:167], v[214:215], 0, s[28:29]
	s_mov_b32 m0, s54
	s_nop 0
	global_load_lds_dwordx4 v[166:167], off
	s_waitcnt vmcnt(8)
	s_waitcnt lgkmcnt(0)
	s_barrier
	s_setprio 1
	s_waitcnt lgkmcnt(0)
	v_mfma_f32_16x16x32_bf16 v[62:65], v[136:139], v[180:183], v[62:65]
	v_mfma_f32_16x16x32_bf16 v[58:61], v[144:147], v[180:183], v[58:61]
	v_mfma_f32_16x16x32_bf16 v[46:49], v[136:139], v[188:191], v[46:49]
	v_mfma_f32_16x16x32_bf16 v[42:45], v[144:147], v[188:191], v[42:45]
	v_mfma_f32_16x16x32_bf16 v[30:33], v[136:139], v[196:199], v[30:33]
	v_mfma_f32_16x16x32_bf16 v[26:29], v[144:147], v[196:199], v[26:29]
	v_mfma_f32_16x16x32_bf16 v[14:17], v[136:139], v[204:207], v[14:17]
	v_mfma_f32_16x16x32_bf16 v[10:13], v[144:147], v[204:207], v[10:13]
	v_mfma_f32_16x16x32_bf16 v[62:65], v[140:143], v[184:187], v[62:65]
	v_mfma_f32_16x16x32_bf16 v[58:61], v[148:151], v[184:187], v[58:61]
	v_mfma_f32_16x16x32_bf16 v[46:49], v[140:143], v[192:195], v[46:49]
	v_mfma_f32_16x16x32_bf16 v[42:45], v[148:151], v[192:195], v[42:45]
	v_mfma_f32_16x16x32_bf16 v[30:33], v[140:143], v[200:203], v[30:33]
	v_mfma_f32_16x16x32_bf16 v[26:29], v[148:151], v[200:203], v[26:29]
	v_mfma_f32_16x16x32_bf16 v[14:17], v[140:143], v[208:211], v[14:17]
	v_mfma_f32_16x16x32_bf16 v[10:13], v[148:151], v[208:211], v[10:13]
	s_setprio 0
	s_setprio 1
	v_mfma_f32_16x16x32_bf16 v[54:57], v[152:155], v[180:183], v[54:57]
	v_mfma_f32_16x16x32_bf16 v[50:53], v[160:163], v[180:183], v[50:53]
	v_mfma_f32_16x16x32_bf16 v[38:41], v[152:155], v[188:191], v[38:41]
	v_mfma_f32_16x16x32_bf16 v[34:37], v[160:163], v[188:191], v[34:37]
	v_mfma_f32_16x16x32_bf16 v[22:25], v[152:155], v[196:199], v[22:25]
	v_mfma_f32_16x16x32_bf16 v[18:21], v[160:163], v[196:199], v[18:21]
	v_mfma_f32_16x16x32_bf16 v[6:9], v[152:155], v[204:207], v[6:9]
	v_mfma_f32_16x16x32_bf16 v[2:5], v[160:163], v[204:207], v[2:5]
	v_mfma_f32_16x16x32_bf16 v[54:57], v[156:159], v[184:187], v[54:57]
	v_mfma_f32_16x16x32_bf16 v[50:53], v[176:179], v[184:187], v[50:53]
	v_mfma_f32_16x16x32_bf16 v[38:41], v[156:159], v[192:195], v[38:41]
	v_mfma_f32_16x16x32_bf16 v[34:37], v[176:179], v[192:195], v[34:37]
	v_mfma_f32_16x16x32_bf16 v[22:25], v[156:159], v[200:203], v[22:25]
	v_mfma_f32_16x16x32_bf16 v[18:21], v[176:179], v[200:203], v[18:21]
	v_mfma_f32_16x16x32_bf16 v[6:9], v[156:159], v[208:211], v[6:9]
	v_mfma_f32_16x16x32_bf16 v[2:5], v[176:179], v[208:211], v[2:5]
	s_setprio 0
	s_barrier
	s_add_i32 s60, s60, 2
	s_add_u32 s58, s58, 0x100
	s_addc_u32 s59, s59, 0
	s_cmp_gt_u32 s60, 41
	s_mov_b64 s[42:43], s[40:41]
	s_cbranch_scc0 .LBB0_1258
	s_and_b64 vcc, exec, s[8:9]
	s_cbranch_vccz .LBB0_1261
	s_barrier
.LBB0_1261:
	v_mov_b32_e32 v136, v246
	s_mov_b32 s10, s12
	s_mov_b32 s46, s52
	s_lshl_b32 s11, s22, 8
	v_and_b32_e32 v137, 15, v136
	s_lshl_b32 s40, s46, 5
	v_bfe_u32 v138, v136, 4, 2
	s_add_i32 s40, s40, s11
	v_lshl_or_b32 v166, s10, 6, v137
	v_readlane_b32 s10, v255, 31
	v_lshl_or_b32 v136, v138, 3, s40
	v_readlane_b32 s11, v255, 32
	v_ashrrev_i32_e32 v137, 31, v136
	v_cmp_eq_u32_e64 s[40:41], 0, v138
	s_lshl_b32 s58, s23, 8
	v_cndmask_b32_e64 v138, 0, 1, s[10:11]
	s_ashr_i32 s47, s46, 31
	v_lshl_add_u64 v[136:137], v[136:137], 1, s[72:73]
	v_cmp_ne_u32_e64 s[42:43], 1, v138
	s_andn2_b64 vcc, exec, s[10:11]
	v_add_u32_e32 v138, s58, v166
	s_cbranch_vccnz .LBB0_1271
; __device__ __forceinline__ unsigned cvt_pk_bf16(float lo, float hi) { unsigned r; asm volatile("s_nop 1\n\tv_cvt_pk_bf16_f32 %0, %1, %2" : "=v"(r) : "v"(lo), "v"(hi)); return r; }
;     __device__ __forceinline__ void operator()(f32x4 (&acc)[2][2][4][2], const Unit& u, int wr, int wc, int fr, int fq) const {
;     ...
;         for (int ai = 0; ai < 2; ++ai) {
;             u32x2 bb[4][2][2];
;             if (!basef) {
; #pragma unroll
;                 for (int m = 0; m < 4; ++m) { const size_t off = (size_t)(u.pm * BM + ai * HALF + wr * 64 + m * 16 + fr) * ldc + col0;
; #pragma unroll
;                     for (int bj = 0; bj < 2; ++bj)
; #pragma unroll
;                         for (int n = 0; n < 2; ++n) bb[m][bj][n] = *(const u32x2*)(baseb + off + bj * HALF + n * 16); }
;             }
; #pragma unroll
;             for (int m = 0; m < 4; ++m) { const size_t row = (size_t)(u.pm * BM + ai * HALF + wr * 64 + m * 16 + fr); const size_t off = row * ldc + col0; float sq = 0.f;
; #pragma unroll
;                 for (int bj = 0; bj < 2; ++bj)
; #pragma unroll
;                     for (int n = 0; n < 2; ++n) { f32x4 bs;
;                         if (basef) bs = *(const f32x4*)(basef + off + bj * HALF + n * 16);
;                         else { const u32x2 b2 = bb[m][bj][n]; bs = (f32x4){bflo(b2.x), bfhi(b2.x), bflo(b2.y), bfhi(b2.y)}; }
;                         const f32x4 v = bs + acc[ai][bj][m][n];
;                         if (out) *(f32x4*)(out + off + bj * HALF + n * 16) = v;
;                         if (hb) { sq += (v.x * v.x + v.y * v.y) + (v.z * v.z + v.w * v.w); *(u32x2*)(hb + off + bj * HALF + n * 16) = (u32x2){cvt_pk_bf16(v.x, v.y), cvt_pk_bf16(v.z, v.w)}; } }
;                 if (hb) { sq += __shfl_xor(sq, 16); sq += __shfl_xor(sq, 32); if (fq == 0) ssq[((size_t)u.pn * T + row) * 4 + wc] = sq; } }
	v_mov_b32_e32 v186, v138
	v_ashrrev_i32_e32 v187, 31, v186
	v_lshlrev_b64 v[194:195], 11, v[186:187]
	v_lshl_add_u64 v[194:195], v[136:137], 0, v[194:195]
	global_load_dwordx4 v[204:207], v[194:195], off
	global_load_dwordx4 v[208:211], v[194:195], off offset:256
	v_add_u32_e32 v188, 16, v138
	v_ashrrev_i32_e32 v189, 31, v188
	v_lshlrev_b64 v[196:197], 11, v[188:189]
	v_lshl_add_u64 v[196:197], v[136:137], 0, v[196:197]
	global_load_dwordx4 v[212:215], v[196:197], off
	global_load_dwordx4 v[216:219], v[196:197], off offset:256
	v_add_u32_e32 v190, 32, v138
	v_ashrrev_i32_e32 v191, 31, v190
	v_lshlrev_b64 v[198:199], 11, v[190:191]
	v_lshl_add_u64 v[198:199], v[136:137], 0, v[198:199]
	global_load_dwordx4 v[220:223], v[198:199], off
	global_load_dwordx4 v[224:227], v[198:199], off offset:256
	v_add_u32_e32 v192, 48, v138
	v_ashrrev_i32_e32 v193, 31, v192
	v_lshlrev_b64 v[200:201], 11, v[192:193]
	v_lshl_add_u64 v[200:201], v[136:137], 0, v[200:201]
	global_load_dwordx4 v[228:231], v[200:201], off
	global_load_dwordx4 v[232:235], v[200:201], off offset:256
	v_xor_b32_e32 v244, 16, v249
	v_xor_b32_e32 v245, 32, v249
	v_lshlrev_b32_e32 v244, 2, v244
	v_lshlrev_b32_e32 v245, 2, v245
	s_waitcnt vmcnt(6)
	v_lshlrev_b32_e32 v202, 16, v204
	v_and_b32_e32 v203, 0xffff0000, v204
	v_pk_add_f32 v[126:127], v[126:127], v[202:203]
	v_mul_f32_e32 v236, v126, v126
	v_mul_f32_e32 v240, v127, v127
	v_lshlrev_b32_e32 v202, 16, v205
	v_and_b32_e32 v203, 0xffff0000, v205
	v_pk_add_f32 v[128:129], v[128:129], v[202:203]
	v_fmac_f32_e32 v236, v128, v128
	v_fmac_f32_e32 v240, v129, v129
	v_lshlrev_b32_e32 v202, 16, v206
	v_and_b32_e32 v203, 0xffff0000, v206
	v_pk_add_f32 v[122:123], v[122:123], v[202:203]
	v_fmac_f32_e32 v236, v122, v122
	v_fmac_f32_e32 v240, v123, v123
	v_lshlrev_b32_e32 v202, 16, v207
	v_and_b32_e32 v203, 0xffff0000, v207
	v_pk_add_f32 v[124:125], v[124:125], v[202:203]
	v_fmac_f32_e32 v236, v124, v124
	v_fmac_f32_e32 v240, v125, v125
	v_cvt_pk_bf16_f32 v204, v126, v127
	v_cvt_pk_bf16_f32 v205, v128, v129
	v_cvt_pk_bf16_f32 v206, v122, v123
	v_cvt_pk_bf16_f32 v207, v124, v125
	global_store_dwordx4 v[194:195], v[204:207], off
	v_lshlrev_b32_e32 v202, 16, v208
	v_and_b32_e32 v203, 0xffff0000, v208
	v_pk_add_f32 v[118:119], v[118:119], v[202:203]
	v_fmac_f32_e32 v236, v118, v118
	v_fmac_f32_e32 v240, v119, v119
	v_lshlrev_b32_e32 v202, 16, v209
	v_and_b32_e32 v203, 0xffff0000, v209
	v_pk_add_f32 v[120:121], v[120:121], v[202:203]
	v_fmac_f32_e32 v236, v120, v120
	v_fmac_f32_e32 v240, v121, v121
	v_lshlrev_b32_e32 v202, 16, v210
	v_and_b32_e32 v203, 0xffff0000, v210
	v_pk_add_f32 v[114:115], v[114:115], v[202:203]
	v_fmac_f32_e32 v236, v114, v114
	v_fmac_f32_e32 v240, v115, v115
	v_lshlrev_b32_e32 v202, 16, v211
	v_and_b32_e32 v203, 0xffff0000, v211
	v_pk_add_f32 v[116:117], v[116:117], v[202:203]
	v_fmac_f32_e32 v236, v116, v116
	v_fmac_f32_e32 v240, v117, v117
	v_cvt_pk_bf16_f32 v208, v118, v119
	v_cvt_pk_bf16_f32 v209, v120, v121
	v_cvt_pk_bf16_f32 v210, v114, v115
	v_cvt_pk_bf16_f32 v211, v116, v117
	global_store_dwordx4 v[194:195], v[208:211], off offset:256
	v_add_f32_e32 v236, v236, v240
	s_waitcnt vmcnt(6)
	v_lshlrev_b32_e32 v202, 16, v212
	v_and_b32_e32 v203, 0xffff0000, v212
	v_pk_add_f32 v[110:111], v[110:111], v[202:203]
	v_mul_f32_e32 v237, v110, v110
	v_mul_f32_e32 v241, v111, v111
	v_lshlrev_b32_e32 v202, 16, v213
	v_and_b32_e32 v203, 0xffff0000, v213
	v_pk_add_f32 v[112:113], v[112:113], v[202:203]
	v_fmac_f32_e32 v237, v112, v112
	v_fmac_f32_e32 v241, v113, v113
	v_lshlrev_b32_e32 v202, 16, v214
	v_and_b32_e32 v203, 0xffff0000, v214
	v_pk_add_f32 v[106:107], v[106:107], v[202:203]
	v_fmac_f32_e32 v237, v106, v106
	v_fmac_f32_e32 v241, v107, v107
	v_lshlrev_b32_e32 v202, 16, v215
	v_and_b32_e32 v203, 0xffff0000, v215
	v_pk_add_f32 v[108:109], v[108:109], v[202:203]
	v_fmac_f32_e32 v237, v108, v108
	v_fmac_f32_e32 v241, v109, v109
	v_cvt_pk_bf16_f32 v212, v110, v111
	v_cvt_pk_bf16_f32 v213, v112, v113
	v_cvt_pk_bf16_f32 v214, v106, v107
	v_cvt_pk_bf16_f32 v215, v108, v109
	global_store_dwordx4 v[196:197], v[212:215], off
	v_lshlrev_b32_e32 v202, 16, v216
	v_and_b32_e32 v203, 0xffff0000, v216
	v_pk_add_f32 v[102:103], v[102:103], v[202:203]
	v_fmac_f32_e32 v237, v102, v102
	v_fmac_f32_e32 v241, v103, v103
	v_lshlrev_b32_e32 v202, 16, v217
	v_and_b32_e32 v203, 0xffff0000, v217
	v_pk_add_f32 v[104:105], v[104:105], v[202:203]
	v_fmac_f32_e32 v237, v104, v104
	v_fmac_f32_e32 v241, v105, v105
	v_lshlrev_b32_e32 v202, 16, v218
	v_and_b32_e32 v203, 0xffff0000, v218
	v_pk_add_f32 v[98:99], v[98:99], v[202:203]
	v_fmac_f32_e32 v237, v98, v98
	v_fmac_f32_e32 v241, v99, v99
	v_lshlrev_b32_e32 v202, 16, v219
	v_and_b32_e32 v203, 0xffff0000, v219
	v_pk_add_f32 v[100:101], v[100:101], v[202:203]
	v_fmac_f32_e32 v237, v100, v100
	v_fmac_f32_e32 v241, v101, v101
	v_cvt_pk_bf16_f32 v216, v102, v103
	v_cvt_pk_bf16_f32 v217, v104, v105
	v_cvt_pk_bf16_f32 v218, v98, v99
	v_cvt_pk_bf16_f32 v219, v100, v101
	global_store_dwordx4 v[196:197], v[216:219], off offset:256
	v_add_f32_e32 v237, v237, v241
	s_waitcnt vmcnt(6)
; __device__ __forceinline__ unsigned cvt_pk_bf16(float lo, float hi) { unsigned r; asm volatile("s_nop 1\n\tv_cvt_pk_bf16_f32 %0, %1, %2" : "=v"(r) : "v"(lo), "v"(hi)); return r; }
;     __device__ __forceinline__ void operator()(f32x4 (&acc)[2][2][4][2], const Unit& u, int wr, int wc, int fr, int fq) const {
;     ...
;             for (int m = 0; m < 4; ++m) { const size_t row = (size_t)(u.pm * BM + ai * HALF + wr * 64 + m * 16 + fr); const size_t off = row * ldc + col0; float sq = 0.f;
; #pragma unroll
;                 for (int bj = 0; bj < 2; ++bj)
; #pragma unroll
;                     for (int n = 0; n < 2; ++n) { f32x4 bs;
;                         if (basef) bs = *(const f32x4*)(basef + off + bj * HALF + n * 16);
;                         else { const u32x2 b2 = bb[m][bj][n]; bs = (f32x4){bflo(b2.x), bfhi(b2.x), bflo(b2.y), bfhi(b2.y)}; }
;                         const f32x4 v = bs + acc[ai][bj][m][n];
;                         if (out) *(f32x4*)(out + off + bj * HALF + n * 16) = v;
;                         if (hb) { sq += (v.x * v.x + v.y * v.y) + (v.z * v.z + v.w * v.w); *(u32x2*)(hb + off + bj * HALF + n * 16) = (u32x2){cvt_pk_bf16(v.x, v.y), cvt_pk_bf16(v.z, v.w)}; } }
;                 if (hb) { sq += __shfl_xor(sq, 16); sq += __shfl_xor(sq, 32); if (fq == 0) ssq[((size_t)u.pn * T + row) * 4 + wc] = sq; } }
	v_lshlrev_b32_e32 v202, 16, v220
	v_and_b32_e32 v203, 0xffff0000, v220
	v_pk_add_f32 v[94:95], v[94:95], v[202:203]
	v_mul_f32_e32 v238, v94, v94
	v_mul_f32_e32 v242, v95, v95
	v_lshlrev_b32_e32 v202, 16, v221
	v_and_b32_e32 v203, 0xffff0000, v221
	v_pk_add_f32 v[96:97], v[96:97], v[202:203]
	v_fmac_f32_e32 v238, v96, v96
	v_fmac_f32_e32 v242, v97, v97
	v_lshlrev_b32_e32 v202, 16, v222
	v_and_b32_e32 v203, 0xffff0000, v222
	v_pk_add_f32 v[90:91], v[90:91], v[202:203]
	v_fmac_f32_e32 v238, v90, v90
	v_fmac_f32_e32 v242, v91, v91
	v_lshlrev_b32_e32 v202, 16, v223
	v_and_b32_e32 v203, 0xffff0000, v223
	v_pk_add_f32 v[92:93], v[92:93], v[202:203]
	v_fmac_f32_e32 v238, v92, v92
	v_fmac_f32_e32 v242, v93, v93
	v_cvt_pk_bf16_f32 v220, v94, v95
	v_cvt_pk_bf16_f32 v221, v96, v97
	v_cvt_pk_bf16_f32 v222, v90, v91
	v_cvt_pk_bf16_f32 v223, v92, v93
	global_store_dwordx4 v[198:199], v[220:223], off
	v_lshlrev_b32_e32 v202, 16, v224
	v_and_b32_e32 v203, 0xffff0000, v224
	v_pk_add_f32 v[86:87], v[86:87], v[202:203]
	v_fmac_f32_e32 v238, v86, v86
	v_fmac_f32_e32 v242, v87, v87
	v_lshlrev_b32_e32 v202, 16, v225
	v_and_b32_e32 v203, 0xffff0000, v225
	v_pk_add_f32 v[88:89], v[88:89], v[202:203]
	v_fmac_f32_e32 v238, v88, v88
	v_fmac_f32_e32 v242, v89, v89
	v_lshlrev_b32_e32 v202, 16, v226
	v_and_b32_e32 v203, 0xffff0000, v226
	v_pk_add_f32 v[82:83], v[82:83], v[202:203]
	v_fmac_f32_e32 v238, v82, v82
	v_fmac_f32_e32 v242, v83, v83
	v_lshlrev_b32_e32 v202, 16, v227
	v_and_b32_e32 v203, 0xffff0000, v227
	v_pk_add_f32 v[84:85], v[84:85], v[202:203]
	v_fmac_f32_e32 v238, v84, v84
	v_fmac_f32_e32 v242, v85, v85
	v_cvt_pk_bf16_f32 v224, v86, v87
	v_cvt_pk_bf16_f32 v225, v88, v89
	v_cvt_pk_bf16_f32 v226, v82, v83
	v_cvt_pk_bf16_f32 v227, v84, v85
	global_store_dwordx4 v[198:199], v[224:227], off offset:256
	v_add_f32_e32 v238, v238, v242
	s_waitcnt vmcnt(6)
	v_lshlrev_b32_e32 v202, 16, v228
	v_and_b32_e32 v203, 0xffff0000, v228
	v_pk_add_f32 v[78:79], v[78:79], v[202:203]
	v_mul_f32_e32 v239, v78, v78
	v_mul_f32_e32 v243, v79, v79
	v_lshlrev_b32_e32 v202, 16, v229
	v_and_b32_e32 v203, 0xffff0000, v229
	v_pk_add_f32 v[80:81], v[80:81], v[202:203]
	v_fmac_f32_e32 v239, v80, v80
	v_fmac_f32_e32 v243, v81, v81
	v_lshlrev_b32_e32 v202, 16, v230
	v_and_b32_e32 v203, 0xffff0000, v230
	v_pk_add_f32 v[74:75], v[74:75], v[202:203]
	v_fmac_f32_e32 v239, v74, v74
	v_fmac_f32_e32 v243, v75, v75
	v_lshlrev_b32_e32 v202, 16, v231
	v_and_b32_e32 v203, 0xffff0000, v231
	v_pk_add_f32 v[76:77], v[76:77], v[202:203]
	v_fmac_f32_e32 v239, v76, v76
	v_fmac_f32_e32 v243, v77, v77
	v_cvt_pk_bf16_f32 v228, v78, v79
	v_cvt_pk_bf16_f32 v229, v80, v81
	v_cvt_pk_bf16_f32 v230, v74, v75
	v_cvt_pk_bf16_f32 v231, v76, v77
	global_store_dwordx4 v[200:201], v[228:231], off
	v_lshlrev_b32_e32 v202, 16, v232
	v_and_b32_e32 v203, 0xffff0000, v232
	v_pk_add_f32 v[70:71], v[70:71], v[202:203]
	v_fmac_f32_e32 v239, v70, v70
	v_fmac_f32_e32 v243, v71, v71
	v_lshlrev_b32_e32 v202, 16, v233
	v_and_b32_e32 v203, 0xffff0000, v233
	v_pk_add_f32 v[72:73], v[72:73], v[202:203]
	v_fmac_f32_e32 v239, v72, v72
	v_fmac_f32_e32 v243, v73, v73
	v_lshlrev_b32_e32 v202, 16, v234
	v_and_b32_e32 v203, 0xffff0000, v234
	v_pk_add_f32 v[66:67], v[66:67], v[202:203]
	v_fmac_f32_e32 v239, v66, v66
	v_fmac_f32_e32 v243, v67, v67
	v_lshlrev_b32_e32 v202, 16, v235
	v_and_b32_e32 v203, 0xffff0000, v235
	v_pk_add_f32 v[68:69], v[68:69], v[202:203]
	v_fmac_f32_e32 v239, v68, v68
	v_fmac_f32_e32 v243, v69, v69
	v_cvt_pk_bf16_f32 v232, v70, v71
	v_cvt_pk_bf16_f32 v233, v72, v73
	v_cvt_pk_bf16_f32 v234, v66, v67
	v_cvt_pk_bf16_f32 v235, v68, v69
	global_store_dwordx4 v[200:201], v[232:235], off offset:256
	v_add_f32_e32 v239, v239, v243
	ds_bpermute_b32 v240, v244, v236
	ds_bpermute_b32 v241, v244, v237
	ds_bpermute_b32 v242, v244, v238
	ds_bpermute_b32 v243, v244, v239
	s_ashr_i32 s23, s22, 31
	s_lshl_b64 s[60:61], s[22:23], 19
	s_add_u32 s60, s70, s60
	s_addc_u32 s61, s71, s61
	s_waitcnt lgkmcnt(0)
	v_add_f32_e32 v236, v236, v240
	v_add_f32_e32 v237, v237, v241
	v_add_f32_e32 v238, v238, v242
	v_add_f32_e32 v239, v239, v243
	ds_bpermute_b32 v240, v245, v236
	ds_bpermute_b32 v241, v245, v237
	ds_bpermute_b32 v242, v245, v238
	ds_bpermute_b32 v243, v245, v239
	v_lshl_add_u64 v[204:205], v[186:187], 4, s[60:61]
	v_lshl_add_u64 v[204:205], s[46:47], 2, v[204:205]
	v_lshl_add_u64 v[212:213], v[188:189], 4, s[60:61]
	v_lshl_add_u64 v[212:213], s[46:47], 2, v[212:213]
	v_lshl_add_u64 v[220:221], v[190:191], 4, s[60:61]
	v_lshl_add_u64 v[220:221], s[46:47], 2, v[220:221]
	v_lshl_add_u64 v[228:229], v[192:193], 4, s[60:61]
	v_lshl_add_u64 v[228:229], s[46:47], 2, v[228:229]
	s_waitcnt lgkmcnt(0)
	v_add_f32_e32 v236, v236, v240
	v_add_f32_e32 v237, v237, v241
	v_add_f32_e32 v238, v238, v242
	v_add_f32_e32 v239, v239, v243
	s_and_saveexec_b64 s[10:11], s[40:41]
	global_store_dword v[204:205], v236, off
	global_store_dword v[212:213], v237, off
	global_store_dword v[220:221], v238, off
	global_store_dword v[228:229], v239, off
	s_or_b64 exec, exec, s[10:11]
; __device__ __forceinline__ unsigned cvt_pk_bf16(float lo, float hi) { unsigned r; asm volatile("s_nop 1\n\tv_cvt_pk_bf16_f32 %0, %1, %2" : "=v"(r) : "v"(lo), "v"(hi)); return r; }
;     __device__ __forceinline__ void operator()(f32x4 (&acc)[2][2][4][2], const Unit& u, int wr, int wc, int fr, int fq) const {
;     ...
;         for (int ai = 0; ai < 2; ++ai) {
;             u32x2 bb[4][2][2];
;             if (!basef) {
; #pragma unroll
;                 for (int m = 0; m < 4; ++m) { const size_t off = (size_t)(u.pm * BM + ai * HALF + wr * 64 + m * 16 + fr) * ldc + col0;
; #pragma unroll
;                     for (int bj = 0; bj < 2; ++bj)
; #pragma unroll
;                         for (int n = 0; n < 2; ++n) bb[m][bj][n] = *(const u32x2*)(baseb + off + bj * HALF + n * 16); }
;             }
; #pragma unroll
;             for (int m = 0; m < 4; ++m) { const size_t row = (size_t)(u.pm * BM + ai * HALF + wr * 64 + m * 16 + fr); const size_t off = row * ldc + col0; float sq = 0.f;
; #pragma unroll
;                 for (int bj = 0; bj < 2; ++bj)
; #pragma unroll
;                     for (int n = 0; n < 2; ++n) { f32x4 bs;
;                         if (basef) bs = *(const f32x4*)(basef + off + bj * HALF + n * 16);
;                         else { const u32x2 b2 = bb[m][bj][n]; bs = (f32x4){bflo(b2.x), bfhi(b2.x), bflo(b2.y), bfhi(b2.y)}; }
;                         const f32x4 v = bs + acc[ai][bj][m][n];
;                         if (out) *(f32x4*)(out + off + bj * HALF + n * 16) = v;
;                         if (hb) { sq += (v.x * v.x + v.y * v.y) + (v.z * v.z + v.w * v.w); *(u32x2*)(hb + off + bj * HALF + n * 16) = (u32x2){cvt_pk_bf16(v.x, v.y), cvt_pk_bf16(v.z, v.w)}; } }
;                 if (hb) { sq += __shfl_xor(sq, 16); sq += __shfl_xor(sq, 32); if (fq == 0) ssq[((size_t)u.pn * T + row) * 4 + wc] = sq; } }
.LBB0_1271:
	s_and_b64 vcc, exec, s[42:43]
	s_cbranch_vccnz .LBB0_1281
	v_add_u32_e32 v186, 128, v138
	v_ashrrev_i32_e32 v187, 31, v186
	v_lshlrev_b64 v[194:195], 11, v[186:187]
	v_lshl_add_u64 v[194:195], v[136:137], 0, v[194:195]
	global_load_dwordx4 v[204:207], v[194:195], off
	global_load_dwordx4 v[208:211], v[194:195], off offset:256
	v_add_u32_e32 v188, 144, v138
	v_ashrrev_i32_e32 v189, 31, v188
	v_lshlrev_b64 v[196:197], 11, v[188:189]
	v_lshl_add_u64 v[196:197], v[136:137], 0, v[196:197]
	global_load_dwordx4 v[212:215], v[196:197], off
	global_load_dwordx4 v[216:219], v[196:197], off offset:256
	v_add_u32_e32 v190, 160, v138
	v_ashrrev_i32_e32 v191, 31, v190
	v_lshlrev_b64 v[198:199], 11, v[190:191]
	v_lshl_add_u64 v[198:199], v[136:137], 0, v[198:199]
	global_load_dwordx4 v[220:223], v[198:199], off
	global_load_dwordx4 v[224:227], v[198:199], off offset:256
	v_add_u32_e32 v192, 176, v138
	v_ashrrev_i32_e32 v193, 31, v192
	v_lshlrev_b64 v[200:201], 11, v[192:193]
	v_lshl_add_u64 v[200:201], v[136:137], 0, v[200:201]
	global_load_dwordx4 v[228:231], v[200:201], off
	global_load_dwordx4 v[232:235], v[200:201], off offset:256
	v_xor_b32_e32 v244, 16, v249
	v_xor_b32_e32 v245, 32, v249
	v_lshlrev_b32_e32 v244, 2, v244
	v_lshlrev_b32_e32 v245, 2, v245
	s_waitcnt vmcnt(6)
	v_lshlrev_b32_e32 v202, 16, v204
	v_and_b32_e32 v203, 0xffff0000, v204
	v_pk_add_f32 v[62:63], v[62:63], v[202:203]
	v_mul_f32_e32 v236, v62, v62
	v_mul_f32_e32 v240, v63, v63
	v_lshlrev_b32_e32 v202, 16, v205
	v_and_b32_e32 v203, 0xffff0000, v205
	v_pk_add_f32 v[64:65], v[64:65], v[202:203]
	v_fmac_f32_e32 v236, v64, v64
	v_fmac_f32_e32 v240, v65, v65
	v_lshlrev_b32_e32 v202, 16, v206
	v_and_b32_e32 v203, 0xffff0000, v206
	v_pk_add_f32 v[58:59], v[58:59], v[202:203]
	v_fmac_f32_e32 v236, v58, v58
	v_fmac_f32_e32 v240, v59, v59
	v_lshlrev_b32_e32 v202, 16, v207
	v_and_b32_e32 v203, 0xffff0000, v207
	v_pk_add_f32 v[60:61], v[60:61], v[202:203]
	v_fmac_f32_e32 v236, v60, v60
	v_fmac_f32_e32 v240, v61, v61
	v_cvt_pk_bf16_f32 v204, v62, v63
	v_cvt_pk_bf16_f32 v205, v64, v65
	v_cvt_pk_bf16_f32 v206, v58, v59
	v_cvt_pk_bf16_f32 v207, v60, v61
	global_store_dwordx4 v[194:195], v[204:207], off
	v_lshlrev_b32_e32 v202, 16, v208
	v_and_b32_e32 v203, 0xffff0000, v208
	v_pk_add_f32 v[54:55], v[54:55], v[202:203]
	v_fmac_f32_e32 v236, v54, v54
	v_fmac_f32_e32 v240, v55, v55
	v_lshlrev_b32_e32 v202, 16, v209
	v_and_b32_e32 v203, 0xffff0000, v209
	v_pk_add_f32 v[56:57], v[56:57], v[202:203]
	v_fmac_f32_e32 v236, v56, v56
	v_fmac_f32_e32 v240, v57, v57
	v_lshlrev_b32_e32 v202, 16, v210
	v_and_b32_e32 v203, 0xffff0000, v210
	v_pk_add_f32 v[50:51], v[50:51], v[202:203]
	v_fmac_f32_e32 v236, v50, v50
	v_fmac_f32_e32 v240, v51, v51
	v_lshlrev_b32_e32 v202, 16, v211
	v_and_b32_e32 v203, 0xffff0000, v211
	v_pk_add_f32 v[52:53], v[52:53], v[202:203]
	v_fmac_f32_e32 v236, v52, v52
	v_fmac_f32_e32 v240, v53, v53
	v_cvt_pk_bf16_f32 v208, v54, v55
	v_cvt_pk_bf16_f32 v209, v56, v57
	v_cvt_pk_bf16_f32 v210, v50, v51
	v_cvt_pk_bf16_f32 v211, v52, v53
	global_store_dwordx4 v[194:195], v[208:211], off offset:256
	v_add_f32_e32 v236, v236, v240
	s_waitcnt vmcnt(6)
	v_lshlrev_b32_e32 v202, 16, v212
	v_and_b32_e32 v203, 0xffff0000, v212
	v_pk_add_f32 v[46:47], v[46:47], v[202:203]
	v_mul_f32_e32 v237, v46, v46
	v_mul_f32_e32 v241, v47, v47
	v_lshlrev_b32_e32 v202, 16, v213
	v_and_b32_e32 v203, 0xffff0000, v213
	v_pk_add_f32 v[48:49], v[48:49], v[202:203]
	v_fmac_f32_e32 v237, v48, v48
	v_fmac_f32_e32 v241, v49, v49
	v_lshlrev_b32_e32 v202, 16, v214
	v_and_b32_e32 v203, 0xffff0000, v214
	v_pk_add_f32 v[42:43], v[42:43], v[202:203]
	v_fmac_f32_e32 v237, v42, v42
	v_fmac_f32_e32 v241, v43, v43
	v_lshlrev_b32_e32 v202, 16, v215
	v_and_b32_e32 v203, 0xffff0000, v215
	v_pk_add_f32 v[44:45], v[44:45], v[202:203]
	v_fmac_f32_e32 v237, v44, v44
	v_fmac_f32_e32 v241, v45, v45
	v_cvt_pk_bf16_f32 v212, v46, v47
	v_cvt_pk_bf16_f32 v213, v48, v49
	v_cvt_pk_bf16_f32 v214, v42, v43
	v_cvt_pk_bf16_f32 v215, v44, v45
	global_store_dwordx4 v[196:197], v[212:215], off
	v_lshlrev_b32_e32 v202, 16, v216
	v_and_b32_e32 v203, 0xffff0000, v216
	v_pk_add_f32 v[38:39], v[38:39], v[202:203]
	v_fmac_f32_e32 v237, v38, v38
	v_fmac_f32_e32 v241, v39, v39
	v_lshlrev_b32_e32 v202, 16, v217
	v_and_b32_e32 v203, 0xffff0000, v217
	v_pk_add_f32 v[40:41], v[40:41], v[202:203]
	v_fmac_f32_e32 v237, v40, v40
	v_fmac_f32_e32 v241, v41, v41
	v_lshlrev_b32_e32 v202, 16, v218
	v_and_b32_e32 v203, 0xffff0000, v218
	v_pk_add_f32 v[34:35], v[34:35], v[202:203]
	v_fmac_f32_e32 v237, v34, v34
	v_fmac_f32_e32 v241, v35, v35
	v_lshlrev_b32_e32 v202, 16, v219
	v_and_b32_e32 v203, 0xffff0000, v219
	v_pk_add_f32 v[36:37], v[36:37], v[202:203]
	v_fmac_f32_e32 v237, v36, v36
	v_fmac_f32_e32 v241, v37, v37
	v_cvt_pk_bf16_f32 v216, v38, v39
	v_cvt_pk_bf16_f32 v217, v40, v41
	v_cvt_pk_bf16_f32 v218, v34, v35
	v_cvt_pk_bf16_f32 v219, v36, v37
	global_store_dwordx4 v[196:197], v[216:219], off offset:256
	v_add_f32_e32 v237, v237, v241
	s_waitcnt vmcnt(6)
; __device__ __forceinline__ unsigned cvt_pk_bf16(float lo, float hi) { unsigned r; asm volatile("s_nop 1\n\tv_cvt_pk_bf16_f32 %0, %1, %2" : "=v"(r) : "v"(lo), "v"(hi)); return r; }
;     __device__ __forceinline__ void operator()(f32x4 (&acc)[2][2][4][2], const Unit& u, int wr, int wc, int fr, int fq) const {
;     ...
;             for (int m = 0; m < 4; ++m) { const size_t row = (size_t)(u.pm * BM + ai * HALF + wr * 64 + m * 16 + fr); const size_t off = row * ldc + col0; float sq = 0.f;
; #pragma unroll
;                 for (int bj = 0; bj < 2; ++bj)
; #pragma unroll
;                     for (int n = 0; n < 2; ++n) { f32x4 bs;
;                         if (basef) bs = *(const f32x4*)(basef + off + bj * HALF + n * 16);
;                         else { const u32x2 b2 = bb[m][bj][n]; bs = (f32x4){bflo(b2.x), bfhi(b2.x), bflo(b2.y), bfhi(b2.y)}; }
;                         const f32x4 v = bs + acc[ai][bj][m][n];
;                         if (out) *(f32x4*)(out + off + bj * HALF + n * 16) = v;
;                         if (hb) { sq += (v.x * v.x + v.y * v.y) + (v.z * v.z + v.w * v.w); *(u32x2*)(hb + off + bj * HALF + n * 16) = (u32x2){cvt_pk_bf16(v.x, v.y), cvt_pk_bf16(v.z, v.w)}; } }
;                 if (hb) { sq += __shfl_xor(sq, 16); sq += __shfl_xor(sq, 32); if (fq == 0) ssq[((size_t)u.pn * T + row) * 4 + wc] = sq; } }
	v_lshlrev_b32_e32 v202, 16, v220
	v_and_b32_e32 v203, 0xffff0000, v220
	v_pk_add_f32 v[30:31], v[30:31], v[202:203]
	v_mul_f32_e32 v238, v30, v30
	v_mul_f32_e32 v242, v31, v31
	v_lshlrev_b32_e32 v202, 16, v221
	v_and_b32_e32 v203, 0xffff0000, v221
	v_pk_add_f32 v[32:33], v[32:33], v[202:203]
	v_fmac_f32_e32 v238, v32, v32
	v_fmac_f32_e32 v242, v33, v33
	v_lshlrev_b32_e32 v202, 16, v222
	v_and_b32_e32 v203, 0xffff0000, v222
	v_pk_add_f32 v[26:27], v[26:27], v[202:203]
	v_fmac_f32_e32 v238, v26, v26
	v_fmac_f32_e32 v242, v27, v27
	v_lshlrev_b32_e32 v202, 16, v223
	v_and_b32_e32 v203, 0xffff0000, v223
	v_pk_add_f32 v[28:29], v[28:29], v[202:203]
	v_fmac_f32_e32 v238, v28, v28
	v_fmac_f32_e32 v242, v29, v29
	v_cvt_pk_bf16_f32 v220, v30, v31
	v_cvt_pk_bf16_f32 v221, v32, v33
	v_cvt_pk_bf16_f32 v222, v26, v27
	v_cvt_pk_bf16_f32 v223, v28, v29
	global_store_dwordx4 v[198:199], v[220:223], off
	v_lshlrev_b32_e32 v202, 16, v224
	v_and_b32_e32 v203, 0xffff0000, v224
	v_pk_add_f32 v[22:23], v[22:23], v[202:203]
	v_fmac_f32_e32 v238, v22, v22
	v_fmac_f32_e32 v242, v23, v23
	v_lshlrev_b32_e32 v202, 16, v225
	v_and_b32_e32 v203, 0xffff0000, v225
	v_pk_add_f32 v[24:25], v[24:25], v[202:203]
	v_fmac_f32_e32 v238, v24, v24
	v_fmac_f32_e32 v242, v25, v25
	v_lshlrev_b32_e32 v202, 16, v226
	v_and_b32_e32 v203, 0xffff0000, v226
	v_pk_add_f32 v[18:19], v[18:19], v[202:203]
	v_fmac_f32_e32 v238, v18, v18
	v_fmac_f32_e32 v242, v19, v19
	v_lshlrev_b32_e32 v202, 16, v227
	v_and_b32_e32 v203, 0xffff0000, v227
	v_pk_add_f32 v[20:21], v[20:21], v[202:203]
	v_fmac_f32_e32 v238, v20, v20
	v_fmac_f32_e32 v242, v21, v21
	v_cvt_pk_bf16_f32 v224, v22, v23
	v_cvt_pk_bf16_f32 v225, v24, v25
	v_cvt_pk_bf16_f32 v226, v18, v19
	v_cvt_pk_bf16_f32 v227, v20, v21
	global_store_dwordx4 v[198:199], v[224:227], off offset:256
	v_add_f32_e32 v238, v238, v242
	s_waitcnt vmcnt(6)
	v_lshlrev_b32_e32 v202, 16, v228
	v_and_b32_e32 v203, 0xffff0000, v228
	v_pk_add_f32 v[14:15], v[14:15], v[202:203]
	v_mul_f32_e32 v239, v14, v14
	v_mul_f32_e32 v243, v15, v15
	v_lshlrev_b32_e32 v202, 16, v229
	v_and_b32_e32 v203, 0xffff0000, v229
	v_pk_add_f32 v[16:17], v[16:17], v[202:203]
	v_fmac_f32_e32 v239, v16, v16
	v_fmac_f32_e32 v243, v17, v17
	v_lshlrev_b32_e32 v202, 16, v230
	v_and_b32_e32 v203, 0xffff0000, v230
	v_pk_add_f32 v[10:11], v[10:11], v[202:203]
	v_fmac_f32_e32 v239, v10, v10
	v_fmac_f32_e32 v243, v11, v11
	v_lshlrev_b32_e32 v202, 16, v231
	v_and_b32_e32 v203, 0xffff0000, v231
	v_pk_add_f32 v[12:13], v[12:13], v[202:203]
	v_fmac_f32_e32 v239, v12, v12
	v_fmac_f32_e32 v243, v13, v13
	v_cvt_pk_bf16_f32 v228, v14, v15
	v_cvt_pk_bf16_f32 v229, v16, v17
	v_cvt_pk_bf16_f32 v230, v10, v11
	v_cvt_pk_bf16_f32 v231, v12, v13
	global_store_dwordx4 v[200:201], v[228:231], off
	v_lshlrev_b32_e32 v202, 16, v232
	v_and_b32_e32 v203, 0xffff0000, v232
	v_pk_add_f32 v[6:7], v[6:7], v[202:203]
	v_fmac_f32_e32 v239, v6, v6
	v_fmac_f32_e32 v243, v7, v7
	v_lshlrev_b32_e32 v202, 16, v233
	v_and_b32_e32 v203, 0xffff0000, v233
	v_pk_add_f32 v[8:9], v[8:9], v[202:203]
	v_fmac_f32_e32 v239, v8, v8
	v_fmac_f32_e32 v243, v9, v9
	v_lshlrev_b32_e32 v202, 16, v234
	v_and_b32_e32 v203, 0xffff0000, v234
	v_pk_add_f32 v[2:3], v[2:3], v[202:203]
	v_fmac_f32_e32 v239, v2, v2
	v_fmac_f32_e32 v243, v3, v3
	v_lshlrev_b32_e32 v202, 16, v235
	v_and_b32_e32 v203, 0xffff0000, v235
	v_pk_add_f32 v[4:5], v[4:5], v[202:203]
	v_fmac_f32_e32 v239, v4, v4
	v_fmac_f32_e32 v243, v5, v5
	v_cvt_pk_bf16_f32 v232, v6, v7
	v_cvt_pk_bf16_f32 v233, v8, v9
	v_cvt_pk_bf16_f32 v234, v2, v3
	v_cvt_pk_bf16_f32 v235, v4, v5
	global_store_dwordx4 v[200:201], v[232:235], off offset:256
	v_add_f32_e32 v239, v239, v243
	ds_bpermute_b32 v240, v244, v236
	ds_bpermute_b32 v241, v244, v237
	ds_bpermute_b32 v242, v244, v238
	ds_bpermute_b32 v243, v244, v239
	s_ashr_i32 s23, s22, 31
	s_lshl_b64 s[60:61], s[22:23], 19
	s_add_u32 s60, s70, s60
	s_addc_u32 s61, s71, s61
	s_waitcnt lgkmcnt(0)
	v_add_f32_e32 v236, v236, v240
	v_add_f32_e32 v237, v237, v241
	v_add_f32_e32 v238, v238, v242
	v_add_f32_e32 v239, v239, v243
	ds_bpermute_b32 v240, v245, v236
	ds_bpermute_b32 v241, v245, v237
	ds_bpermute_b32 v242, v245, v238
	ds_bpermute_b32 v243, v245, v239
	v_lshl_add_u64 v[204:205], v[186:187], 4, s[60:61]
	v_lshl_add_u64 v[204:205], s[46:47], 2, v[204:205]
	v_lshl_add_u64 v[212:213], v[188:189], 4, s[60:61]
	v_lshl_add_u64 v[212:213], s[46:47], 2, v[212:213]
	v_lshl_add_u64 v[220:221], v[190:191], 4, s[60:61]
	v_lshl_add_u64 v[220:221], s[46:47], 2, v[220:221]
	v_lshl_add_u64 v[228:229], v[192:193], 4, s[60:61]
	v_lshl_add_u64 v[228:229], s[46:47], 2, v[228:229]
	s_waitcnt lgkmcnt(0)
	v_add_f32_e32 v236, v236, v240
	v_add_f32_e32 v237, v237, v241
	v_add_f32_e32 v238, v238, v242
	v_add_f32_e32 v239, v239, v243
	s_and_saveexec_b64 s[10:11], s[40:41]
	global_store_dword v[204:205], v236, off
	global_store_dword v[212:213], v237, off
	global_store_dword v[220:221], v238, off
	global_store_dword v[228:229], v239, off
	s_or_b64 exec, exec, s[10:11]
